# speedup vs baseline: 1.0152x; 1.0152x over previous
.LBB0_64:
	ds_read_b128 v[142:145], v135
	ds_read_b128 v[166:169], v139
	ds_read_b128 v[170:173], v135 offset:2048
	ds_read_b128 v[174:177], v139 offset:2048
	s_add_u32 s18, s16, 0x40080
	s_addc_u32 s19, s17, 0
	s_add_u32 s20, s16, 0x60080
	s_addc_u32 s21, s17, 0
	s_cmp_eq_u32 s3, 12
	s_cselect_b32 vcc_lo, s11, s15
	s_cselect_b32 vcc_hi, s10, s14
	s_cselect_b32 s82, s9, s13
	s_cselect_b32 s83, s8, s12
	s_nop 0
	ds_read_b128 v[178:181], v136
	ds_read_b128 v[182:185], v137
	ds_read_b128 v[186:189], v136 offset:2048
	ds_read_b128 v[190:193], v137 offset:2048
	ds_read_b128 v[194:197], v136 offset:4096
	ds_read_b128 v[198:201], v137 offset:4096
	ds_read_b128 v[202:205], v136 offset:6144
	ds_read_b128 v[206:209], v137 offset:6144
	s_mov_b32 m0, s72
	s_nop 0
	global_load_lds_dwordx4 v130, s[18:19]
	s_nop 0
	s_mov_b32 m0, s73
	s_nop 0
	global_load_lds_dwordx4 v130, s[20:21]
	ds_read_b128 v[210:213], v135 offset:16384
	ds_read_b128 v[214:217], v139 offset:16384
	ds_read_b128 v[218:221], v135 offset:18432
	ds_read_b128 v[222:225], v139 offset:18432
	s_waitcnt vmcnt(8) lgkmcnt(0)
	s_barrier
	s_waitcnt lgkmcnt(7)
	v_mfma_f32_16x16x32_bf16 v[124:127], v[142:145], v[178:181], v[124:127]
	v_mfma_f32_16x16x32_bf16 v[124:127], v[166:169], v[182:185], v[124:127]
	s_waitcnt lgkmcnt(5)
	v_mfma_f32_16x16x32_bf16 v[120:123], v[170:173], v[178:181], v[120:123]
	v_mfma_f32_16x16x32_bf16 v[120:123], v[174:177], v[182:185], v[120:123]
	s_waitcnt lgkmcnt(3)
	v_mfma_f32_16x16x32_bf16 v[88:91], v[218:221], v[178:181], v[88:91]
	v_mfma_f32_16x16x32_bf16 v[88:91], v[222:225], v[182:185], v[88:91]
	s_waitcnt lgkmcnt(1)
	v_mfma_f32_16x16x32_bf16 v[92:95], v[210:213], v[178:181], v[92:95]
	v_mfma_f32_16x16x32_bf16 v[92:95], v[214:217], v[182:185], v[92:95]
	v_mfma_f32_16x16x32_bf16 v[84:87], v[210:213], v[186:189], v[84:87]
	v_mfma_f32_16x16x32_bf16 v[84:87], v[214:217], v[190:193], v[84:87]
	v_mfma_f32_16x16x32_bf16 v[80:83], v[218:221], v[186:189], v[80:83]
	v_mfma_f32_16x16x32_bf16 v[80:83], v[222:225], v[190:193], v[80:83]
	v_mfma_f32_16x16x32_bf16 v[112:115], v[170:173], v[186:189], v[112:115]
	v_mfma_f32_16x16x32_bf16 v[112:115], v[174:177], v[190:193], v[112:115]
	s_waitcnt lgkmcnt(0)
	v_mfma_f32_16x16x32_bf16 v[116:119], v[142:145], v[186:189], v[116:119]
	v_mfma_f32_16x16x32_bf16 v[116:119], v[166:169], v[190:193], v[116:119]
	s_waitcnt lgkmcnt(3)
	v_mfma_f32_16x16x32_bf16 v[108:111], v[142:145], v[194:197], v[108:111]
	s_waitcnt lgkmcnt(1)
	v_mfma_f32_16x16x32_bf16 v[108:111], v[166:169], v[198:201], v[108:111]
	v_mfma_f32_16x16x32_bf16 v[104:107], v[170:173], v[194:197], v[104:107]
	v_mfma_f32_16x16x32_bf16 v[104:107], v[174:177], v[198:201], v[104:107]
	v_mfma_f32_16x16x32_bf16 v[72:75], v[218:221], v[194:197], v[72:75]
	v_mfma_f32_16x16x32_bf16 v[72:75], v[222:225], v[198:201], v[72:75]
	v_mfma_f32_16x16x32_bf16 v[76:79], v[210:213], v[194:197], v[76:79]
	v_mfma_f32_16x16x32_bf16 v[76:79], v[214:217], v[198:201], v[76:79]
	v_mfma_f32_16x16x32_bf16 v[68:71], v[210:213], v[202:205], v[68:71]
	s_waitcnt lgkmcnt(0)
	v_mfma_f32_16x16x32_bf16 v[68:71], v[214:217], v[206:209], v[68:71]
	v_mfma_f32_16x16x32_bf16 v[64:67], v[218:221], v[202:205], v[64:67]
	v_mfma_f32_16x16x32_bf16 v[64:67], v[222:225], v[206:209], v[64:67]
	v_mfma_f32_16x16x32_bf16 v[96:99], v[170:173], v[202:205], v[96:99]
	v_mfma_f32_16x16x32_bf16 v[96:99], v[174:177], v[206:209], v[96:99]
	v_mfma_f32_16x16x32_bf16 v[100:103], v[142:145], v[202:205], v[100:103]
	v_mfma_f32_16x16x32_bf16 v[100:103], v[166:169], v[206:209], v[100:103]
	s_barrier
	s_cselect_b32 s70, 0, s5
	s_lshl_b64 s[92:93], s[70:71], 1
	s_add_u32 s18, vcc_hi, s92
	s_addc_u32 s19, vcc_lo, s93
	s_add_u32 s20, s18, 0x20000
	s_mov_b32 m0, s26
	s_nop 0
	global_load_lds_dwordx4 v130, s[18:19]
	s_addc_u32 s21, s19, 0
	s_mov_b32 m0, s27
	s_nop 0
	global_load_lds_dwordx4 v130, s[20:21]
	ds_read_b128 v[178:181], v136 offset:16384
	ds_read_b128 v[182:185], v137 offset:16384
	ds_read_b128 v[186:189], v136 offset:18432
	ds_read_b128 v[190:193], v137 offset:18432
	ds_read_b128 v[194:197], v136 offset:20480
	ds_read_b128 v[198:201], v137 offset:20480
	ds_read_b128 v[202:205], v136 offset:22528
	ds_read_b128 v[206:209], v137 offset:22528
	s_add_u32 s20, s83, s92
	s_addc_u32 s21, s82, s93
	s_add_u32 s82, s20, 0x20000
	s_mov_b32 m0, s25
	s_nop 0
	global_load_lds_dwordx4 v130, s[20:21]
	s_addc_u32 s83, s21, 0
	s_mov_b32 m0, s28
	s_nop 0
	global_load_lds_dwordx4 v130, s[82:83]
	s_add_u32 vcc_hi, vcc_hi, 0x40000
	s_addc_u32 vcc_lo, vcc_lo, 0
	s_add_u32 s82, vcc_hi, s92
	s_addc_u32 s83, vcc_lo, s93
	s_add_u32 s92, s82, 0x20000
	s_mov_b32 m0, s29
	s_nop 0
	global_load_lds_dwordx4 v130, s[82:83]
	s_addc_u32 s93, s83, 0
	s_mov_b32 m0, s30
	s_nop 0
	global_load_lds_dwordx4 v130, s[92:93]
	s_waitcnt vmcnt(8) lgkmcnt(0)
	s_barrier
	s_waitcnt lgkmcnt(7)
	v_mfma_f32_16x16x32_bf16 v[60:63], v[142:145], v[178:181], v[60:63]
	v_mfma_f32_16x16x32_bf16 v[60:63], v[166:169], v[182:185], v[60:63]
	s_waitcnt lgkmcnt(5)
	v_mfma_f32_16x16x32_bf16 v[56:59], v[170:173], v[178:181], v[56:59]
	v_mfma_f32_16x16x32_bf16 v[56:59], v[174:177], v[182:185], v[56:59]
	s_waitcnt lgkmcnt(3)
	v_mfma_f32_16x16x32_bf16 v[24:27], v[218:221], v[178:181], v[24:27]
	v_mfma_f32_16x16x32_bf16 v[24:27], v[222:225], v[182:185], v[24:27]
	s_waitcnt lgkmcnt(1)
	v_mfma_f32_16x16x32_bf16 v[28:31], v[210:213], v[178:181], v[28:31]
	v_mfma_f32_16x16x32_bf16 v[28:31], v[214:217], v[182:185], v[28:31]
	v_mfma_f32_16x16x32_bf16 v[20:23], v[210:213], v[186:189], v[20:23]
	v_mfma_f32_16x16x32_bf16 v[20:23], v[214:217], v[190:193], v[20:23]
	v_mfma_f32_16x16x32_bf16 v[16:19], v[218:221], v[186:189], v[16:19]
	v_mfma_f32_16x16x32_bf16 v[16:19], v[222:225], v[190:193], v[16:19]
	v_mfma_f32_16x16x32_bf16 v[48:51], v[170:173], v[186:189], v[48:51]
	v_mfma_f32_16x16x32_bf16 v[48:51], v[174:177], v[190:193], v[48:51]
	s_waitcnt lgkmcnt(0)
	v_mfma_f32_16x16x32_bf16 v[52:55], v[142:145], v[186:189], v[52:55]
	v_mfma_f32_16x16x32_bf16 v[52:55], v[166:169], v[190:193], v[52:55]
	v_mfma_f32_16x16x32_bf16 v[44:47], v[142:145], v[194:197], v[44:47]
	v_mfma_f32_16x16x32_bf16 v[44:47], v[166:169], v[198:201], v[44:47]
	v_mfma_f32_16x16x32_bf16 v[40:43], v[170:173], v[194:197], v[40:43]
	v_mfma_f32_16x16x32_bf16 v[40:43], v[174:177], v[198:201], v[40:43]
	v_mfma_f32_16x16x32_bf16 v[8:11], v[218:221], v[194:197], v[8:11]
	v_mfma_f32_16x16x32_bf16 v[8:11], v[222:225], v[198:201], v[8:11]
	v_mfma_f32_16x16x32_bf16 v[12:15], v[210:213], v[194:197], v[12:15]
	v_mfma_f32_16x16x32_bf16 v[12:15], v[214:217], v[198:201], v[12:15]
	v_mfma_f32_16x16x32_bf16 v[4:7], v[210:213], v[202:205], v[4:7]
	v_mfma_f32_16x16x32_bf16 v[4:7], v[214:217], v[206:209], v[4:7]
	v_mfma_f32_16x16x32_bf16 v[0:3], v[218:221], v[202:205], v[0:3]
	v_mfma_f32_16x16x32_bf16 v[0:3], v[222:225], v[206:209], v[0:3]
	v_mfma_f32_16x16x32_bf16 v[32:35], v[170:173], v[202:205], v[32:35]
	v_mfma_f32_16x16x32_bf16 v[32:35], v[174:177], v[206:209], v[32:35]
	v_mfma_f32_16x16x32_bf16 v[36:39], v[142:145], v[202:205], v[36:39]
	v_mfma_f32_16x16x32_bf16 v[36:39], v[166:169], v[206:209], v[36:39]
	s_barrier
	ds_read_b128 v[142:145], v135 offset:32768
	ds_read_b128 v[166:169], v139 offset:32768
	ds_read_b128 v[170:173], v135 offset:34816
	ds_read_b128 v[174:177], v139 offset:34816
	ds_read_b128 v[178:181], v136 offset:32768
	ds_read_b128 v[182:185], v137 offset:32768
	ds_read_b128 v[186:189], v136 offset:34816
	ds_read_b128 v[190:193], v137 offset:34816
	ds_read_b128 v[194:197], v136 offset:36864
	ds_read_b128 v[198:201], v137 offset:36864
	ds_read_b128 v[202:205], v136 offset:38912
	ds_read_b128 v[206:209], v137 offset:38912
	s_add_u32 s82, s20, 0x40000
	s_addc_u32 s83, s21, 0
	s_add_u32 s92, s20, 0x60000
	s_mov_b32 m0, s31
	s_nop 0
	global_load_lds_dwordx4 v130, s[82:83]
	s_addc_u32 s93, s21, 0
	s_mov_b32 m0, s34
	s_nop 0
	global_load_lds_dwordx4 v130, s[92:93]
	ds_read_b128 v[210:213], v135 offset:49152
	ds_read_b128 v[214:217], v139 offset:49152
	ds_read_b128 v[218:221], v135 offset:51200
	ds_read_b128 v[222:225], v139 offset:51200
	s_waitcnt vmcnt(8) lgkmcnt(0)
	s_barrier
	s_waitcnt lgkmcnt(7)
	v_mfma_f32_16x16x32_bf16 v[124:127], v[142:145], v[178:181], v[124:127]
	v_mfma_f32_16x16x32_bf16 v[124:127], v[166:169], v[182:185], v[124:127]
	s_waitcnt lgkmcnt(5)
	v_mfma_f32_16x16x32_bf16 v[120:123], v[170:173], v[178:181], v[120:123]
	v_mfma_f32_16x16x32_bf16 v[120:123], v[174:177], v[182:185], v[120:123]
	s_waitcnt lgkmcnt(3)
	v_mfma_f32_16x16x32_bf16 v[88:91], v[218:221], v[178:181], v[88:91]
	v_mfma_f32_16x16x32_bf16 v[88:91], v[222:225], v[182:185], v[88:91]
	s_waitcnt lgkmcnt(1)
	v_mfma_f32_16x16x32_bf16 v[92:95], v[210:213], v[178:181], v[92:95]
	v_mfma_f32_16x16x32_bf16 v[92:95], v[214:217], v[182:185], v[92:95]
	v_mfma_f32_16x16x32_bf16 v[84:87], v[210:213], v[186:189], v[84:87]
	v_mfma_f32_16x16x32_bf16 v[84:87], v[214:217], v[190:193], v[84:87]
	v_mfma_f32_16x16x32_bf16 v[80:83], v[218:221], v[186:189], v[80:83]
	v_mfma_f32_16x16x32_bf16 v[80:83], v[222:225], v[190:193], v[80:83]
	v_mfma_f32_16x16x32_bf16 v[112:115], v[170:173], v[186:189], v[112:115]
	v_mfma_f32_16x16x32_bf16 v[112:115], v[174:177], v[190:193], v[112:115]
	s_waitcnt lgkmcnt(0)
	v_mfma_f32_16x16x32_bf16 v[116:119], v[142:145], v[186:189], v[116:119]
	v_mfma_f32_16x16x32_bf16 v[116:119], v[166:169], v[190:193], v[116:119]
	s_waitcnt lgkmcnt(3)
	v_mfma_f32_16x16x32_bf16 v[108:111], v[142:145], v[194:197], v[108:111]
	s_waitcnt lgkmcnt(1)
	v_mfma_f32_16x16x32_bf16 v[108:111], v[166:169], v[198:201], v[108:111]
	v_mfma_f32_16x16x32_bf16 v[104:107], v[170:173], v[194:197], v[104:107]
	v_mfma_f32_16x16x32_bf16 v[104:107], v[174:177], v[198:201], v[104:107]
	v_mfma_f32_16x16x32_bf16 v[72:75], v[218:221], v[194:197], v[72:75]
	v_mfma_f32_16x16x32_bf16 v[72:75], v[222:225], v[198:201], v[72:75]
	v_mfma_f32_16x16x32_bf16 v[76:79], v[210:213], v[194:197], v[76:79]
	v_mfma_f32_16x16x32_bf16 v[76:79], v[214:217], v[198:201], v[76:79]
	v_mfma_f32_16x16x32_bf16 v[68:71], v[210:213], v[202:205], v[68:71]
	s_waitcnt lgkmcnt(0)
	v_mfma_f32_16x16x32_bf16 v[68:71], v[214:217], v[206:209], v[68:71]
	v_mfma_f32_16x16x32_bf16 v[64:67], v[218:221], v[202:205], v[64:67]
	v_mfma_f32_16x16x32_bf16 v[64:67], v[222:225], v[206:209], v[64:67]
	v_mfma_f32_16x16x32_bf16 v[96:99], v[170:173], v[202:205], v[96:99]
	v_mfma_f32_16x16x32_bf16 v[96:99], v[174:177], v[206:209], v[96:99]
	v_mfma_f32_16x16x32_bf16 v[100:103], v[142:145], v[202:205], v[100:103]
	v_mfma_f32_16x16x32_bf16 v[100:103], v[166:169], v[206:209], v[100:103]
	s_barrier
; template <int N, int K, int EPI>
; __device__ void gemm_phase(const u16* __restrict__ A, const u16* __restrict__ Bt, const EpiArgs ea, char* smem, int tid) {
;     ...
;     for (int t = 0; t < nt; t += 2) {
;       const bool lastit = (t == nt - 2);
;       const u16* A2 = lastit ? Abn : Ab;
;       const u16* B2 = lastit ? Bbn : Bb;
;       const int k2 = lastit ? 0 : t + 2;
;       BODY(Ab, t + 1, A2, B2, k2, k2 + 1);
	s_or_b32 s70, s70, 64
	s_add_u32 s82, s18, 0x80
	s_addc_u32 s83, s19, 0
	s_add_u32 s18, s18, 0x20080
	s_mov_b32 m0, s35
	s_nop 0
	global_load_lds_dwordx4 v130, s[82:83]
	s_addc_u32 s19, s19, 0
	s_mov_b32 m0, s36
	s_nop 0
	global_load_lds_dwordx4 v130, s[18:19]
	ds_read_b128 v[178:181], v136 offset:49152
	ds_read_b128 v[182:185], v137 offset:49152
	ds_read_b128 v[186:189], v136 offset:51200
	ds_read_b128 v[190:193], v137 offset:51200
	ds_read_b128 v[194:197], v136 offset:53248
	ds_read_b128 v[198:201], v137 offset:53248
	ds_read_b128 v[202:205], v136 offset:55296
	ds_read_b128 v[206:209], v137 offset:55296
	s_add_u32 s18, s20, 0x80
	s_addc_u32 s19, s21, 0
	s_add_u32 s20, s20, 0x20080
	s_mov_b32 m0, s37
	s_nop 0
	global_load_lds_dwordx4 v130, s[18:19]
	s_addc_u32 s21, s21, 0
	s_mov_b32 m0, s42
	s_nop 0
	global_load_lds_dwordx4 v130, s[20:21]
	s_lshl_b64 s[18:19], s[70:71], 1
	s_add_u32 s18, vcc_hi, s18
	s_addc_u32 s19, vcc_lo, s19
	s_add_u32 s20, s18, 0x20000
	s_mov_b32 m0, s43
	s_nop 0
	global_load_lds_dwordx4 v130, s[18:19]
	s_addc_u32 s21, s19, 0
	s_mov_b32 m0, s66
	s_nop 0
	global_load_lds_dwordx4 v130, s[20:21]
	s_waitcnt vmcnt(8) lgkmcnt(0)
	s_barrier
	s_waitcnt lgkmcnt(7)
	v_mfma_f32_16x16x32_bf16 v[60:63], v[142:145], v[178:181], v[60:63]
	v_mfma_f32_16x16x32_bf16 v[60:63], v[166:169], v[182:185], v[60:63]
	s_waitcnt lgkmcnt(5)
	v_mfma_f32_16x16x32_bf16 v[56:59], v[170:173], v[178:181], v[56:59]
	v_mfma_f32_16x16x32_bf16 v[56:59], v[174:177], v[182:185], v[56:59]
	s_waitcnt lgkmcnt(3)
	v_mfma_f32_16x16x32_bf16 v[24:27], v[218:221], v[178:181], v[24:27]
	v_mfma_f32_16x16x32_bf16 v[24:27], v[222:225], v[182:185], v[24:27]
	s_waitcnt lgkmcnt(1)
	v_mfma_f32_16x16x32_bf16 v[28:31], v[210:213], v[178:181], v[28:31]
	v_mfma_f32_16x16x32_bf16 v[28:31], v[214:217], v[182:185], v[28:31]
	v_mfma_f32_16x16x32_bf16 v[20:23], v[210:213], v[186:189], v[20:23]
	v_mfma_f32_16x16x32_bf16 v[20:23], v[214:217], v[190:193], v[20:23]
	v_mfma_f32_16x16x32_bf16 v[16:19], v[218:221], v[186:189], v[16:19]
	v_mfma_f32_16x16x32_bf16 v[16:19], v[222:225], v[190:193], v[16:19]
	v_mfma_f32_16x16x32_bf16 v[48:51], v[170:173], v[186:189], v[48:51]
	v_mfma_f32_16x16x32_bf16 v[48:51], v[174:177], v[190:193], v[48:51]
	s_waitcnt lgkmcnt(0)
	v_mfma_f32_16x16x32_bf16 v[52:55], v[142:145], v[186:189], v[52:55]
	v_mfma_f32_16x16x32_bf16 v[52:55], v[166:169], v[190:193], v[52:55]
	v_mfma_f32_16x16x32_bf16 v[44:47], v[142:145], v[194:197], v[44:47]
	v_mfma_f32_16x16x32_bf16 v[44:47], v[166:169], v[198:201], v[44:47]
	v_mfma_f32_16x16x32_bf16 v[40:43], v[170:173], v[194:197], v[40:43]
	v_mfma_f32_16x16x32_bf16 v[40:43], v[174:177], v[198:201], v[40:43]
	v_mfma_f32_16x16x32_bf16 v[8:11], v[218:221], v[194:197], v[8:11]
	v_mfma_f32_16x16x32_bf16 v[8:11], v[222:225], v[198:201], v[8:11]
	v_mfma_f32_16x16x32_bf16 v[12:15], v[210:213], v[194:197], v[12:15]
	v_mfma_f32_16x16x32_bf16 v[12:15], v[214:217], v[198:201], v[12:15]
	v_mfma_f32_16x16x32_bf16 v[4:7], v[210:213], v[202:205], v[4:7]
	v_mfma_f32_16x16x32_bf16 v[4:7], v[214:217], v[206:209], v[4:7]
	v_mfma_f32_16x16x32_bf16 v[0:3], v[218:221], v[202:205], v[0:3]
	v_mfma_f32_16x16x32_bf16 v[0:3], v[222:225], v[206:209], v[0:3]
	v_mfma_f32_16x16x32_bf16 v[32:35], v[170:173], v[202:205], v[32:35]
	v_mfma_f32_16x16x32_bf16 v[32:35], v[174:177], v[206:209], v[32:35]
	v_mfma_f32_16x16x32_bf16 v[36:39], v[142:145], v[202:205], v[36:39]
	v_mfma_f32_16x16x32_bf16 v[36:39], v[166:169], v[206:209], v[36:39]
	s_add_i32 s3, s3, 2
	s_addk_i32 s5, 0x80
	s_add_u32 s16, s16, 0x100
	s_addc_u32 s17, s17, 0
	s_cmp_gt_u32 s3, 13
	s_barrier
	s_cbranch_scc0 .LBB0_64
; #define WAIT_V(n) asm volatile("s_waitcnt vmcnt(" #n ")" ::: "memory")
; #define BAR __builtin_amdgcn_s_barrier()
; template <int N, int K, int EPI>
; __device__ void gemm_phase(const u16* __restrict__ A, const u16* __restrict__ Bt, const EpiArgs ea, char* smem, int tid) {
;     ...
;       } else if constexpr (EPI == EPI_F) {
;         u16* f = ea.o0;
; #pragma unroll
;         for (int ai = 0; ai < 2; ++ai)
; #pragma unroll
;           for (int bj = 0; bj < 2; ++bj)
; #pragma unroll
;             for (int m = 0; m < 4; ++m) {
;               const int row = brow + ai * HALF + wr * 64 + m * 16 + fr_e;
;               const int col = pn * BM + bj * HALF + wc * 32 + fq_e * 8;
;               const f32x4 v0 = acc[ai][bj][m][0], v1 = acc[ai][bj][m][1];
;               u32x4 o = {pk_bf16(v0[0], v0[1]), pk_bf16(v0[2], v0[3]), pk_bf16(v1[0], v1[1]), pk_bf16(v1[2], v1[3])};
;               *(u32x4*)(f + (size_t)row * N + col) = o;
;             }
;     ...
;     if (!has_next) break;
; #pragma unroll
;     for (int ai = 0; ai < 2; ++ai)
; #pragma unroll
;       for (int bj = 0; bj < 2; ++bj)
; #pragma unroll
;         for (int m = 0; m < 4; ++m)
; #pragma unroll
;           for (int n = 0; n < 2; ++n) acc[ai][bj][m][n] = f32x4{0.f, 0.f, 0.f, 0.f};
;     v = vn; pm = pmn; pn = pnn; Ab = Abn; Bb = Bbn;
;   }
;   WAIT_V(0);
;   if (wr == 0) BAR;
	s_lshl_b32 s3, s24, 8
	v_mov_b32_e32 v128, v131
	v_mov_b32_e32 v129, v132
	s_add_i32 s3, s3, s67
	v_cvt_pk_bf16_f32 v124, v124, v125
	v_cvt_pk_bf16_f32 v125, v126, v127
	v_cvt_pk_bf16_f32 v126, v120, v121
	v_cvt_pk_bf16_f32 v127, v122, v123
	v_cvt_pk_bf16_f32 v116, v116, v117
	s_nop 0
	v_add_u32_e32 v142, s3, v128
	s_lshl_b32 s3, s95, 8
	s_or_b32 s3, s3, s88
	v_lshl_add_u32 v144, v129, 3, s3
	v_ashrrev_i32_e32 v145, 31, v144
	v_ashrrev_i32_e32 v143, 31, v142
	v_lshl_add_u64 v[128:129], v[144:145], 1, s[64:65]
	v_lshlrev_b64 v[120:121], 11, v[142:143]
	v_lshl_add_u64 v[122:123], v[128:129], 0, v[120:121]
	global_store_dwordx4 v[122:123], v[124:127], off
	v_add_u32_e32 v122, 16, v142
	v_ashrrev_i32_e32 v123, 31, v122
	v_cvt_pk_bf16_f32 v117, v118, v119
	v_cvt_pk_bf16_f32 v118, v112, v113
	v_lshlrev_b64 v[112:113], 11, v[122:123]
	v_cvt_pk_bf16_f32 v119, v114, v115
	v_lshl_add_u64 v[114:115], v[128:129], 0, v[112:113]
	global_store_dwordx4 v[114:115], v[116:119], off
	v_add_u32_e32 v114, 32, v142
	v_ashrrev_i32_e32 v115, 31, v114
	v_cvt_pk_bf16_f32 v108, v108, v109
	v_cvt_pk_bf16_f32 v109, v110, v111
	v_cvt_pk_bf16_f32 v110, v104, v105
	v_lshlrev_b64 v[104:105], 11, v[114:115]
	v_cvt_pk_bf16_f32 v111, v106, v107
	v_lshl_add_u64 v[106:107], v[128:129], 0, v[104:105]
	global_store_dwordx4 v[106:107], v[108:111], off
	v_add_u32_e32 v106, 48, v142
	v_ashrrev_i32_e32 v107, 31, v106
	v_cvt_pk_bf16_f32 v100, v100, v101
	v_cvt_pk_bf16_f32 v101, v102, v103
	v_cvt_pk_bf16_f32 v102, v96, v97
	v_lshlrev_b64 v[96:97], 11, v[106:107]
	v_cvt_pk_bf16_f32 v103, v98, v99
	v_lshl_add_u64 v[98:99], v[128:129], 0, v[96:97]
	global_store_dwordx4 v[98:99], v[100:103], off
	v_add_u32_e32 v98, 0x80, v144
	v_ashrrev_i32_e32 v99, 31, v98
	v_lshl_add_u64 v[98:99], v[98:99], 1, s[64:65]
	v_cvt_pk_bf16_f32 v68, v68, v69
	v_cvt_pk_bf16_f32 v69, v70, v71
	v_cvt_pk_bf16_f32 v70, v64, v65
	v_lshl_add_u64 v[64:65], v[98:99], 0, v[96:97]
	v_cvt_pk_bf16_f32 v71, v66, v67
	global_store_dwordx4 v[64:65], v[68:71], off
	v_add_u32_e32 v64, 0x80, v142
	v_ashrrev_i32_e32 v65, 31, v64
	v_cvt_pk_bf16_f32 v60, v60, v61
	v_cvt_pk_bf16_f32 v61, v62, v63
	v_cvt_pk_bf16_f32 v62, v56, v57
	v_lshlrev_b64 v[56:57], 11, v[64:65]
	v_cvt_pk_bf16_f32 v92, v92, v93
	v_cvt_pk_bf16_f32 v93, v94, v95
	v_cvt_pk_bf16_f32 v94, v88, v89
	v_lshl_add_u64 v[88:89], v[98:99], 0, v[120:121]
	v_cvt_pk_bf16_f32 v84, v84, v85
	v_cvt_pk_bf16_f32 v85, v86, v87
	v_cvt_pk_bf16_f32 v86, v80, v81
	v_lshl_add_u64 v[80:81], v[98:99], 0, v[112:113]
	v_cvt_pk_bf16_f32 v76, v76, v77
	v_cvt_pk_bf16_f32 v77, v78, v79
	v_cvt_pk_bf16_f32 v78, v72, v73
	v_lshl_add_u64 v[72:73], v[98:99], 0, v[104:105]
	v_cvt_pk_bf16_f32 v63, v58, v59
	v_lshl_add_u64 v[58:59], v[128:129], 0, v[56:57]
	v_cvt_pk_bf16_f32 v95, v90, v91
	global_store_dwordx4 v[88:89], v[92:95], off
	v_cvt_pk_bf16_f32 v87, v82, v83
	global_store_dwordx4 v[80:81], v[84:87], off
	v_cvt_pk_bf16_f32 v79, v74, v75
	global_store_dwordx4 v[72:73], v[76:79], off
	global_store_dwordx4 v[58:59], v[60:63], off
	v_add_u32_e32 v58, 0x90, v142
	v_ashrrev_i32_e32 v59, 31, v58
	v_cvt_pk_bf16_f32 v52, v52, v53
	v_cvt_pk_bf16_f32 v53, v54, v55
	v_cvt_pk_bf16_f32 v54, v48, v49
	v_lshlrev_b64 v[48:49], 11, v[58:59]
	v_cvt_pk_bf16_f32 v55, v50, v51
	v_lshl_add_u64 v[50:51], v[128:129], 0, v[48:49]
	global_store_dwordx4 v[50:51], v[52:55], off
	v_add_u32_e32 v50, 0xa0, v142
	v_ashrrev_i32_e32 v51, 31, v50
	v_cvt_pk_bf16_f32 v44, v44, v45
	v_cvt_pk_bf16_f32 v45, v46, v47
	v_cvt_pk_bf16_f32 v46, v40, v41
	v_lshlrev_b64 v[40:41], 11, v[50:51]
	v_cvt_pk_bf16_f32 v47, v42, v43
	v_lshl_add_u64 v[42:43], v[128:129], 0, v[40:41]
	global_store_dwordx4 v[42:43], v[44:47], off
	v_add_u32_e32 v42, 0xb0, v142
	v_ashrrev_i32_e32 v43, 31, v42
	v_cvt_pk_bf16_f32 v36, v36, v37
	v_cvt_pk_bf16_f32 v37, v38, v39
	v_cvt_pk_bf16_f32 v38, v32, v33
	v_lshlrev_b64 v[32:33], 11, v[42:43]
	v_cvt_pk_bf16_f32 v39, v34, v35
	v_lshl_add_u64 v[34:35], v[128:129], 0, v[32:33]
	v_cvt_pk_bf16_f32 v28, v28, v29
	v_cvt_pk_bf16_f32 v29, v30, v31
	v_cvt_pk_bf16_f32 v30, v24, v25
	v_lshl_add_u64 v[24:25], v[98:99], 0, v[56:57]
	v_cvt_pk_bf16_f32 v20, v20, v21
	v_cvt_pk_bf16_f32 v21, v22, v23
	v_cvt_pk_bf16_f32 v22, v16, v17
	v_lshl_add_u64 v[16:17], v[98:99], 0, v[48:49]
	v_cvt_pk_bf16_f32 v12, v12, v13
	v_cvt_pk_bf16_f32 v13, v14, v15
	v_cvt_pk_bf16_f32 v14, v8, v9
	v_lshl_add_u64 v[8:9], v[98:99], 0, v[40:41]
	v_cvt_pk_bf16_f32 v4, v4, v5
	v_cvt_pk_bf16_f32 v5, v6, v7
	v_cvt_pk_bf16_f32 v6, v0, v1
	v_lshl_add_u64 v[0:1], v[98:99], 0, v[32:33]
	s_and_b64 vcc, exec, s[0:1]
	s_mov_b32 s24, s2
	s_mov_b32 s95, s4
	s_mov_b64 s[14:15], s[10:11]
	s_mov_b64 s[12:13], s[8:9]
	global_store_dwordx4 v[34:35], v[36:39], off
	v_cvt_pk_bf16_f32 v31, v26, v27
	global_store_dwordx4 v[24:25], v[28:31], off
	v_cvt_pk_bf16_f32 v23, v18, v19
	global_store_dwordx4 v[16:17], v[20:23], off
	v_cvt_pk_bf16_f32 v15, v10, v11
	global_store_dwordx4 v[8:9], v[12:15], off
	v_cvt_pk_bf16_f32 v7, v2, v3
	global_store_dwordx4 v[0:1], v[4:7], off
	s_cbranch_vccz .LBB0_61
	s_setprio 0
	s_waitcnt vmcnt(0)
	v_readlane_b32 s0, v226, 16
	v_readlane_b32 s36, v226, 30
	v_readlane_b32 s18, v226, 22
	v_readlane_b32 s92, v226, 20
	s_cmpk_gt_u32 s0, 0xff
	v_readlane_b32 s37, v226, 31
	v_readlane_b32 s31, v226, 34
	v_readlane_b32 s42, v226, 29
	v_readlane_b32 s43, v226, 28
	v_readlane_b32 s66, v226, 27
	v_readlane_b32 s67, v226, 26
	v_readlane_b32 s19, v226, 23
	v_readlane_b32 s93, v226, 21
	s_cbranch_scc1 .LBB0_68
	s_barrier

.LBB0_110:
	ds_read_b128 v[128:131], v169
	ds_read_b128 v[134:137], v173
	ds_read_b128 v[138:141], v169 offset:2048
	ds_read_b128 v[142:145], v173 offset:2048
	s_add_u32 s16, s14, 0x40080
	s_addc_u32 s17, s15, 0
	s_add_u32 s18, s14, 0x60080
	s_addc_u32 s19, s15, 0
	s_cmp_eq_u32 s3, 12
	s_cselect_b32 s82, s11, s13
	s_cselect_b32 s83, s10, s12
	s_cselect_b32 s88, s9, s5
	s_cselect_b32 s89, s8, s4
	s_nop 0
	ds_read_b128 v[176:179], v170
	ds_read_b128 v[180:183], v171
	ds_read_b128 v[184:187], v170 offset:2048
	ds_read_b128 v[188:191], v171 offset:2048
	ds_read_b128 v[192:195], v170 offset:4096
	ds_read_b128 v[196:199], v171 offset:4096
	ds_read_b128 v[200:203], v170 offset:6144
	ds_read_b128 v[204:207], v171 offset:6144
	s_mov_b32 m0, s66
	s_nop 0
	global_load_lds_dwordx4 v165, s[16:17]
	s_nop 0
	s_mov_b32 m0, s67
	s_nop 0
	global_load_lds_dwordx4 v165, s[18:19]
	ds_read_b128 v[208:211], v169 offset:16384
	ds_read_b128 v[212:215], v173 offset:16384
	ds_read_b128 v[216:219], v169 offset:18432
	ds_read_b128 v[220:223], v173 offset:18432
	s_waitcnt vmcnt(8) lgkmcnt(0)
	s_barrier
	s_waitcnt lgkmcnt(7)
	v_mfma_f32_16x16x32_bf16 v[124:127], v[128:131], v[176:179], v[124:127]
	v_mfma_f32_16x16x32_bf16 v[124:127], v[134:137], v[180:183], v[124:127]
	s_waitcnt lgkmcnt(5)
	v_mfma_f32_16x16x32_bf16 v[120:123], v[138:141], v[176:179], v[120:123]
	v_mfma_f32_16x16x32_bf16 v[120:123], v[142:145], v[180:183], v[120:123]
	s_waitcnt lgkmcnt(3)
	v_mfma_f32_16x16x32_bf16 v[88:91], v[216:219], v[176:179], v[88:91]
	v_mfma_f32_16x16x32_bf16 v[88:91], v[220:223], v[180:183], v[88:91]
	s_waitcnt lgkmcnt(1)
	v_mfma_f32_16x16x32_bf16 v[92:95], v[208:211], v[176:179], v[92:95]
	v_mfma_f32_16x16x32_bf16 v[92:95], v[212:215], v[180:183], v[92:95]
	v_mfma_f32_16x16x32_bf16 v[84:87], v[208:211], v[184:187], v[84:87]
	v_mfma_f32_16x16x32_bf16 v[84:87], v[212:215], v[188:191], v[84:87]
	v_mfma_f32_16x16x32_bf16 v[80:83], v[216:219], v[184:187], v[80:83]
	v_mfma_f32_16x16x32_bf16 v[80:83], v[220:223], v[188:191], v[80:83]
	v_mfma_f32_16x16x32_bf16 v[112:115], v[138:141], v[184:187], v[112:115]
	v_mfma_f32_16x16x32_bf16 v[112:115], v[142:145], v[188:191], v[112:115]
	s_waitcnt lgkmcnt(0)
	v_mfma_f32_16x16x32_bf16 v[116:119], v[128:131], v[184:187], v[116:119]
	v_mfma_f32_16x16x32_bf16 v[116:119], v[134:137], v[188:191], v[116:119]
	s_waitcnt lgkmcnt(3)
	v_mfma_f32_16x16x32_bf16 v[108:111], v[128:131], v[192:195], v[108:111]
	s_waitcnt lgkmcnt(1)
	v_mfma_f32_16x16x32_bf16 v[108:111], v[134:137], v[196:199], v[108:111]
	v_mfma_f32_16x16x32_bf16 v[104:107], v[138:141], v[192:195], v[104:107]
	v_mfma_f32_16x16x32_bf16 v[104:107], v[142:145], v[196:199], v[104:107]
	v_mfma_f32_16x16x32_bf16 v[72:75], v[216:219], v[192:195], v[72:75]
	v_mfma_f32_16x16x32_bf16 v[72:75], v[220:223], v[196:199], v[72:75]
	v_mfma_f32_16x16x32_bf16 v[76:79], v[208:211], v[192:195], v[76:79]
	v_mfma_f32_16x16x32_bf16 v[76:79], v[212:215], v[196:199], v[76:79]
	v_mfma_f32_16x16x32_bf16 v[68:71], v[208:211], v[200:203], v[68:71]
	s_waitcnt lgkmcnt(0)
	v_mfma_f32_16x16x32_bf16 v[68:71], v[212:215], v[204:207], v[68:71]
	v_mfma_f32_16x16x32_bf16 v[64:67], v[216:219], v[200:203], v[64:67]
	v_mfma_f32_16x16x32_bf16 v[64:67], v[220:223], v[204:207], v[64:67]
	v_mfma_f32_16x16x32_bf16 v[96:99], v[138:141], v[200:203], v[96:99]
	v_mfma_f32_16x16x32_bf16 v[96:99], v[142:145], v[204:207], v[96:99]
	v_mfma_f32_16x16x32_bf16 v[100:103], v[128:131], v[200:203], v[100:103]
	v_mfma_f32_16x16x32_bf16 v[100:103], v[134:137], v[204:207], v[100:103]
	s_barrier
	s_cselect_b32 s70, 0, s7
	s_lshl_b64 s[92:93], s[70:71], 1
	s_add_u32 s16, s83, s92
	s_addc_u32 s17, s82, s93
	s_add_u32 s18, s16, 0x20000
	s_mov_b32 m0, s24
	s_nop 0
	global_load_lds_dwordx4 v165, s[16:17]
	s_addc_u32 s19, s17, 0
	s_mov_b32 m0, s25
	s_nop 0
	global_load_lds_dwordx4 v165, s[18:19]
	ds_read_b128 v[176:179], v170 offset:16384
	ds_read_b128 v[180:183], v171 offset:16384
	ds_read_b128 v[184:187], v170 offset:18432
	ds_read_b128 v[188:191], v171 offset:18432
	ds_read_b128 v[192:195], v170 offset:20480
	ds_read_b128 v[196:199], v171 offset:20480
	ds_read_b128 v[200:203], v170 offset:22528
	ds_read_b128 v[204:207], v171 offset:22528
	s_add_u32 s18, s89, s92
	s_addc_u32 s19, s88, s93
	s_add_u32 s88, s18, 0x20000
	s_mov_b32 m0, s23
	s_nop 0
	global_load_lds_dwordx4 v165, s[18:19]
	s_addc_u32 s89, s19, 0
	s_mov_b32 m0, s26
	s_nop 0
	global_load_lds_dwordx4 v165, s[88:89]
	s_add_u32 s83, s83, 0x40000
	s_addc_u32 s82, s82, 0
	s_add_u32 s88, s83, s92
	s_addc_u32 s89, s82, s93
	s_add_u32 s92, s88, 0x20000
	s_mov_b32 m0, s27
	s_nop 0
	global_load_lds_dwordx4 v165, s[88:89]
	s_addc_u32 s93, s89, 0
	s_mov_b32 m0, s28
	s_nop 0
	global_load_lds_dwordx4 v165, s[92:93]
	s_waitcnt vmcnt(8) lgkmcnt(0)
	s_barrier
	s_waitcnt lgkmcnt(7)
	v_mfma_f32_16x16x32_bf16 v[60:63], v[128:131], v[176:179], v[60:63]
	v_mfma_f32_16x16x32_bf16 v[60:63], v[134:137], v[180:183], v[60:63]
	s_waitcnt lgkmcnt(5)
	v_mfma_f32_16x16x32_bf16 v[56:59], v[138:141], v[176:179], v[56:59]
	v_mfma_f32_16x16x32_bf16 v[56:59], v[142:145], v[180:183], v[56:59]
	s_waitcnt lgkmcnt(3)
	v_mfma_f32_16x16x32_bf16 v[24:27], v[216:219], v[176:179], v[24:27]
	v_mfma_f32_16x16x32_bf16 v[24:27], v[220:223], v[180:183], v[24:27]
	s_waitcnt lgkmcnt(1)
	v_mfma_f32_16x16x32_bf16 v[28:31], v[208:211], v[176:179], v[28:31]
	v_mfma_f32_16x16x32_bf16 v[28:31], v[212:215], v[180:183], v[28:31]
	v_mfma_f32_16x16x32_bf16 v[20:23], v[208:211], v[184:187], v[20:23]
	v_mfma_f32_16x16x32_bf16 v[20:23], v[212:215], v[188:191], v[20:23]
	v_mfma_f32_16x16x32_bf16 v[16:19], v[216:219], v[184:187], v[16:19]
	v_mfma_f32_16x16x32_bf16 v[16:19], v[220:223], v[188:191], v[16:19]
	v_mfma_f32_16x16x32_bf16 v[48:51], v[138:141], v[184:187], v[48:51]
	v_mfma_f32_16x16x32_bf16 v[48:51], v[142:145], v[188:191], v[48:51]
	s_waitcnt lgkmcnt(0)
	v_mfma_f32_16x16x32_bf16 v[52:55], v[128:131], v[184:187], v[52:55]
	v_mfma_f32_16x16x32_bf16 v[52:55], v[134:137], v[188:191], v[52:55]
	v_mfma_f32_16x16x32_bf16 v[44:47], v[128:131], v[192:195], v[44:47]
	v_mfma_f32_16x16x32_bf16 v[44:47], v[134:137], v[196:199], v[44:47]
	v_mfma_f32_16x16x32_bf16 v[40:43], v[138:141], v[192:195], v[40:43]
	v_mfma_f32_16x16x32_bf16 v[40:43], v[142:145], v[196:199], v[40:43]
	v_mfma_f32_16x16x32_bf16 v[8:11], v[216:219], v[192:195], v[8:11]
	v_mfma_f32_16x16x32_bf16 v[8:11], v[220:223], v[196:199], v[8:11]
	v_mfma_f32_16x16x32_bf16 v[12:15], v[208:211], v[192:195], v[12:15]
	v_mfma_f32_16x16x32_bf16 v[12:15], v[212:215], v[196:199], v[12:15]
	v_mfma_f32_16x16x32_bf16 v[4:7], v[208:211], v[200:203], v[4:7]
	v_mfma_f32_16x16x32_bf16 v[4:7], v[212:215], v[204:207], v[4:7]
	v_mfma_f32_16x16x32_bf16 v[0:3], v[216:219], v[200:203], v[0:3]
	v_mfma_f32_16x16x32_bf16 v[0:3], v[220:223], v[204:207], v[0:3]
	v_mfma_f32_16x16x32_bf16 v[32:35], v[138:141], v[200:203], v[32:35]
	v_mfma_f32_16x16x32_bf16 v[32:35], v[142:145], v[204:207], v[32:35]
	v_mfma_f32_16x16x32_bf16 v[36:39], v[128:131], v[200:203], v[36:39]
	v_mfma_f32_16x16x32_bf16 v[36:39], v[134:137], v[204:207], v[36:39]
	s_barrier
	ds_read_b128 v[128:131], v169 offset:32768
	ds_read_b128 v[134:137], v173 offset:32768
	ds_read_b128 v[138:141], v169 offset:34816
	ds_read_b128 v[142:145], v173 offset:34816
	ds_read_b128 v[176:179], v170 offset:32768
	ds_read_b128 v[180:183], v171 offset:32768
	ds_read_b128 v[184:187], v170 offset:34816
	ds_read_b128 v[188:191], v171 offset:34816
	ds_read_b128 v[192:195], v170 offset:36864
	ds_read_b128 v[196:199], v171 offset:36864
	ds_read_b128 v[200:203], v170 offset:38912
	ds_read_b128 v[204:207], v171 offset:38912
	s_add_u32 s88, s18, 0x40000
	s_addc_u32 s89, s19, 0
	s_add_u32 s92, s18, 0x60000
	s_mov_b32 m0, s29
	s_nop 0
	global_load_lds_dwordx4 v165, s[88:89]
	s_addc_u32 s93, s19, 0
	s_mov_b32 m0, s30
	s_nop 0
	global_load_lds_dwordx4 v165, s[92:93]
	ds_read_b128 v[208:211], v169 offset:49152
	ds_read_b128 v[212:215], v173 offset:49152
	ds_read_b128 v[216:219], v169 offset:51200
	ds_read_b128 v[220:223], v173 offset:51200
	s_waitcnt vmcnt(8) lgkmcnt(0)
	s_barrier
	s_waitcnt lgkmcnt(7)
	v_mfma_f32_16x16x32_bf16 v[124:127], v[128:131], v[176:179], v[124:127]
	v_mfma_f32_16x16x32_bf16 v[124:127], v[134:137], v[180:183], v[124:127]
	s_waitcnt lgkmcnt(5)
	v_mfma_f32_16x16x32_bf16 v[120:123], v[138:141], v[176:179], v[120:123]
	v_mfma_f32_16x16x32_bf16 v[120:123], v[142:145], v[180:183], v[120:123]
	s_waitcnt lgkmcnt(3)
	v_mfma_f32_16x16x32_bf16 v[88:91], v[216:219], v[176:179], v[88:91]
	v_mfma_f32_16x16x32_bf16 v[88:91], v[220:223], v[180:183], v[88:91]
	s_waitcnt lgkmcnt(1)
	v_mfma_f32_16x16x32_bf16 v[92:95], v[208:211], v[176:179], v[92:95]
	v_mfma_f32_16x16x32_bf16 v[92:95], v[212:215], v[180:183], v[92:95]
	v_mfma_f32_16x16x32_bf16 v[84:87], v[208:211], v[184:187], v[84:87]
	v_mfma_f32_16x16x32_bf16 v[84:87], v[212:215], v[188:191], v[84:87]
	v_mfma_f32_16x16x32_bf16 v[80:83], v[216:219], v[184:187], v[80:83]
	v_mfma_f32_16x16x32_bf16 v[80:83], v[220:223], v[188:191], v[80:83]
	v_mfma_f32_16x16x32_bf16 v[112:115], v[138:141], v[184:187], v[112:115]
	v_mfma_f32_16x16x32_bf16 v[112:115], v[142:145], v[188:191], v[112:115]
	s_waitcnt lgkmcnt(0)
	v_mfma_f32_16x16x32_bf16 v[116:119], v[128:131], v[184:187], v[116:119]
	v_mfma_f32_16x16x32_bf16 v[116:119], v[134:137], v[188:191], v[116:119]
	s_waitcnt lgkmcnt(3)
	v_mfma_f32_16x16x32_bf16 v[108:111], v[128:131], v[192:195], v[108:111]
	s_waitcnt lgkmcnt(1)
	v_mfma_f32_16x16x32_bf16 v[108:111], v[134:137], v[196:199], v[108:111]
	v_mfma_f32_16x16x32_bf16 v[104:107], v[138:141], v[192:195], v[104:107]
	v_mfma_f32_16x16x32_bf16 v[104:107], v[142:145], v[196:199], v[104:107]
	v_mfma_f32_16x16x32_bf16 v[72:75], v[216:219], v[192:195], v[72:75]
	v_mfma_f32_16x16x32_bf16 v[72:75], v[220:223], v[196:199], v[72:75]
	v_mfma_f32_16x16x32_bf16 v[76:79], v[208:211], v[192:195], v[76:79]
	v_mfma_f32_16x16x32_bf16 v[76:79], v[212:215], v[196:199], v[76:79]
	v_mfma_f32_16x16x32_bf16 v[68:71], v[208:211], v[200:203], v[68:71]
	s_waitcnt lgkmcnt(0)
	v_mfma_f32_16x16x32_bf16 v[68:71], v[212:215], v[204:207], v[68:71]
	v_mfma_f32_16x16x32_bf16 v[64:67], v[216:219], v[200:203], v[64:67]
	v_mfma_f32_16x16x32_bf16 v[64:67], v[220:223], v[204:207], v[64:67]
	v_mfma_f32_16x16x32_bf16 v[96:99], v[138:141], v[200:203], v[96:99]
	v_mfma_f32_16x16x32_bf16 v[96:99], v[142:145], v[204:207], v[96:99]
	v_mfma_f32_16x16x32_bf16 v[100:103], v[128:131], v[200:203], v[100:103]
	v_mfma_f32_16x16x32_bf16 v[100:103], v[134:137], v[204:207], v[100:103]
	s_barrier
; template <int N, int K, int EPI>
; __device__ void gemm_phase(const u16* __restrict__ A, const u16* __restrict__ Bt, const EpiArgs ea, char* smem, int tid) {
;     ...
;         if (pn == 4 || pn == 5) {
;           u16* vt = ea.o2;
; #pragma unroll
;           for (int ai = 0; ai < 2; ++ai)
; #pragma unroll
;             for (int bj = 0; bj < 2; ++bj)
; #pragma unroll
;               for (int m = 0; m < 4; ++m)
; #pragma unroll
;                 for (int n = 0; n < 2; ++n) {
;                   f32x4 vv = acc[ai][bj][m][n];
;                   const bool b0 = fr_e & 1, b1 = fr_e & 2;
;                   { float sA = b0 ? vv[0] : vv[1], sB = b0 ? vv[2] : vv[3];
;                     float rA = __shfl_xor(sA, 1), rB = __shfl_xor(sB, 1);
;                     if (b0) { vv[0] = rA; vv[2] = rB; } else { vv[1] = rA; vv[3] = rB; } }
;                   { float sC = b1 ? vv[0] : vv[2], sD = b1 ? vv[1] : vv[3];
;                     float rC = __shfl_xor(sC, 2), rD = __shfl_xor(sD, 2);
;                     if (b1) { vv[0] = rC; vv[1] = rD; } else { vv[2] = rC; vv[3] = rD; } }
;                   int row = brow + ai * HALF + wr * 64 + m * 16 + (fr_e & ~3);
;                   int col = (pn - 4) * 256 + bj * HALF + wc * 32 + fq_e * 8 + n * 4 + (fr_e & 3);
;                   int b = row >> 12, sq = row & 4095, hh = col >> 6, dh = col & 63;
;                   u32x2 o = {pk_bf16(vv[0], vv[1]), pk_bf16(vv[2], vv[3])};
;                   *(u32x2*)(vt + ((size_t)(b * 8 + hh) * 64 + dh) * SEQ + sq) = o;
;                 }
;         } else {
;           u16* base; float sc = 1.f; int cbase; bool headed;
;           if (pn < 2) { base = ea.o0; sc = QSCALE; cbase = pn * 256; headed = true; }
;           else if (pn < 4) { base = ea.o1; cbase = (pn - 2) * 256; headed = true; }
;           else { base = ea.o3; cbase = (pn - 6) * 256; headed = false; }
	s_or_b32 s70, s70, 64
	s_add_u32 s88, s16, 0x80
	s_addc_u32 s89, s17, 0
	s_add_u32 s16, s16, 0x20080
	s_mov_b32 m0, s31
	s_nop 0
	global_load_lds_dwordx4 v165, s[88:89]
	s_addc_u32 s17, s17, 0
	s_mov_b32 m0, s34
	s_nop 0
	global_load_lds_dwordx4 v165, s[16:17]
	ds_read_b128 v[176:179], v170 offset:49152
	ds_read_b128 v[180:183], v171 offset:49152
	ds_read_b128 v[184:187], v170 offset:51200
	ds_read_b128 v[188:191], v171 offset:51200
	ds_read_b128 v[192:195], v170 offset:53248
	ds_read_b128 v[196:199], v171 offset:53248
	ds_read_b128 v[200:203], v170 offset:55296
	ds_read_b128 v[204:207], v171 offset:55296
	s_add_u32 s16, s18, 0x80
	s_addc_u32 s17, s19, 0
	s_add_u32 s18, s18, 0x20080
	s_mov_b32 m0, s35
	s_nop 0
	global_load_lds_dwordx4 v165, s[16:17]
	s_addc_u32 s19, s19, 0
	s_mov_b32 m0, s36
	s_nop 0
	global_load_lds_dwordx4 v165, s[18:19]
	s_lshl_b64 s[16:17], s[70:71], 1
	s_add_u32 s16, s83, s16
	s_addc_u32 s17, s82, s17
	s_add_u32 s18, s16, 0x20000
	s_mov_b32 m0, s37
	s_nop 0
	global_load_lds_dwordx4 v165, s[16:17]
	s_addc_u32 s19, s17, 0
	s_mov_b32 m0, s42
	s_nop 0
	global_load_lds_dwordx4 v165, s[18:19]
	s_waitcnt vmcnt(8) lgkmcnt(0)
	s_barrier
	s_waitcnt lgkmcnt(7)
	v_mfma_f32_16x16x32_bf16 v[60:63], v[128:131], v[176:179], v[60:63]
	v_mfma_f32_16x16x32_bf16 v[60:63], v[134:137], v[180:183], v[60:63]
	s_waitcnt lgkmcnt(5)
	v_mfma_f32_16x16x32_bf16 v[56:59], v[138:141], v[176:179], v[56:59]
	v_mfma_f32_16x16x32_bf16 v[56:59], v[142:145], v[180:183], v[56:59]
	s_waitcnt lgkmcnt(3)
	v_mfma_f32_16x16x32_bf16 v[24:27], v[216:219], v[176:179], v[24:27]
	v_mfma_f32_16x16x32_bf16 v[24:27], v[220:223], v[180:183], v[24:27]
	s_waitcnt lgkmcnt(1)
	v_mfma_f32_16x16x32_bf16 v[28:31], v[208:211], v[176:179], v[28:31]
	v_mfma_f32_16x16x32_bf16 v[28:31], v[212:215], v[180:183], v[28:31]
	v_mfma_f32_16x16x32_bf16 v[20:23], v[208:211], v[184:187], v[20:23]
	v_mfma_f32_16x16x32_bf16 v[20:23], v[212:215], v[188:191], v[20:23]
	v_mfma_f32_16x16x32_bf16 v[16:19], v[216:219], v[184:187], v[16:19]
	v_mfma_f32_16x16x32_bf16 v[16:19], v[220:223], v[188:191], v[16:19]
	v_mfma_f32_16x16x32_bf16 v[48:51], v[138:141], v[184:187], v[48:51]
	v_mfma_f32_16x16x32_bf16 v[48:51], v[142:145], v[188:191], v[48:51]
	s_waitcnt lgkmcnt(0)
	v_mfma_f32_16x16x32_bf16 v[52:55], v[128:131], v[184:187], v[52:55]
	v_mfma_f32_16x16x32_bf16 v[52:55], v[134:137], v[188:191], v[52:55]
	v_mfma_f32_16x16x32_bf16 v[44:47], v[128:131], v[192:195], v[44:47]
	v_mfma_f32_16x16x32_bf16 v[44:47], v[134:137], v[196:199], v[44:47]
	v_mfma_f32_16x16x32_bf16 v[40:43], v[138:141], v[192:195], v[40:43]
	v_mfma_f32_16x16x32_bf16 v[40:43], v[142:145], v[196:199], v[40:43]
	v_mfma_f32_16x16x32_bf16 v[8:11], v[216:219], v[192:195], v[8:11]
	v_mfma_f32_16x16x32_bf16 v[8:11], v[220:223], v[196:199], v[8:11]
	v_mfma_f32_16x16x32_bf16 v[12:15], v[208:211], v[192:195], v[12:15]
	v_mfma_f32_16x16x32_bf16 v[12:15], v[212:215], v[196:199], v[12:15]
	v_mfma_f32_16x16x32_bf16 v[4:7], v[208:211], v[200:203], v[4:7]
	v_mfma_f32_16x16x32_bf16 v[4:7], v[212:215], v[204:207], v[4:7]
	v_mfma_f32_16x16x32_bf16 v[0:3], v[216:219], v[200:203], v[0:3]
	v_mfma_f32_16x16x32_bf16 v[0:3], v[220:223], v[204:207], v[0:3]
	v_mfma_f32_16x16x32_bf16 v[32:35], v[138:141], v[200:203], v[32:35]
	v_mfma_f32_16x16x32_bf16 v[32:35], v[142:145], v[204:207], v[32:35]
	v_mfma_f32_16x16x32_bf16 v[36:39], v[128:131], v[200:203], v[36:39]
	v_mfma_f32_16x16x32_bf16 v[36:39], v[134:137], v[204:207], v[36:39]
	s_add_i32 s3, s3, 2
	s_addk_i32 s7, 0x80
	s_add_u32 s14, s14, 0x100
	s_addc_u32 s15, s15, 0
	s_cmp_gt_u32 s3, 13
	s_barrier
	s_cbranch_scc0 .LBB0_110
	s_lshl_b32 s3, s97, 8
	s_and_b32 s4, s96, -2
	v_mov_b32_e32 v176, v167
	v_mov_b32_e32 v132, v166
	s_cmp_lg_u32 s4, 4
	s_mov_b64 s[4:5], -1
	s_mov_b32 s19, 0x3ffc0
	s_cbranch_scc0 .LBB0_184
	s_cmp_gt_i32 s96, 1
	s_mov_b64 s[14:15], -1
	s_cbranch_scc0 .LBB0_117
	s_lshl_b32 s7, s96, 8
	s_cmp_gt_u32 s96, 3
	s_mov_b64 s[4:5], -1
	s_cbranch_scc0 .LBB0_115
	s_add_i32 s18, s7, 0xfffffa00
	s_mov_b64 s[4:5], 0

.LBB0_220:
	ds_read_b128 v[142:145], v135
	ds_read_b128 v[166:169], v139
	ds_read_b128 v[170:173], v135 offset:2048
	ds_read_b128 v[174:177], v139 offset:2048
	s_add_u32 s12, s10, 0xb0080
	s_addc_u32 s13, s11, 0
	s_add_u32 s14, s10, 0x108080
	s_addc_u32 s15, s11, 0
	s_cmp_eq_u32 s89, 40
	s_cselect_b32 s82, s5, s9
	s_cselect_b32 s83, s4, s8
	s_cselect_b32 s92, s3, s7
	s_cselect_b32 s93, s2, s6
	s_nop 0
	ds_read_b128 v[178:181], v136
	ds_read_b128 v[182:185], v137
	ds_read_b128 v[186:189], v136 offset:2048
	ds_read_b128 v[190:193], v137 offset:2048
	ds_read_b128 v[194:197], v136 offset:4096
	ds_read_b128 v[198:201], v137 offset:4096
	ds_read_b128 v[202:205], v136 offset:6144
	ds_read_b128 v[206:209], v137 offset:6144
	s_mov_b32 m0, s36
	s_nop 0
	global_load_lds_dwordx4 v130, s[12:13]
	s_nop 0
	s_mov_b32 m0, s37
	s_nop 0
	global_load_lds_dwordx4 v130, s[14:15]
	ds_read_b128 v[210:213], v135 offset:16384
	ds_read_b128 v[214:217], v139 offset:16384
	ds_read_b128 v[218:221], v135 offset:18432
	ds_read_b128 v[222:225], v139 offset:18432
	s_waitcnt vmcnt(8) lgkmcnt(0)
	s_barrier
	s_waitcnt lgkmcnt(7)
	v_mfma_f32_16x16x32_bf16 v[124:127], v[142:145], v[178:181], v[124:127]
	v_mfma_f32_16x16x32_bf16 v[124:127], v[166:169], v[182:185], v[124:127]
	s_waitcnt lgkmcnt(5)
	v_mfma_f32_16x16x32_bf16 v[120:123], v[170:173], v[178:181], v[120:123]
	v_mfma_f32_16x16x32_bf16 v[120:123], v[174:177], v[182:185], v[120:123]
	s_waitcnt lgkmcnt(3)
	v_mfma_f32_16x16x32_bf16 v[88:91], v[218:221], v[178:181], v[88:91]
	v_mfma_f32_16x16x32_bf16 v[88:91], v[222:225], v[182:185], v[88:91]
	s_waitcnt lgkmcnt(1)
	v_mfma_f32_16x16x32_bf16 v[92:95], v[210:213], v[178:181], v[92:95]
	v_mfma_f32_16x16x32_bf16 v[92:95], v[214:217], v[182:185], v[92:95]
	v_mfma_f32_16x16x32_bf16 v[84:87], v[210:213], v[186:189], v[84:87]
	v_mfma_f32_16x16x32_bf16 v[84:87], v[214:217], v[190:193], v[84:87]
	v_mfma_f32_16x16x32_bf16 v[80:83], v[218:221], v[186:189], v[80:83]
	v_mfma_f32_16x16x32_bf16 v[80:83], v[222:225], v[190:193], v[80:83]
	v_mfma_f32_16x16x32_bf16 v[112:115], v[170:173], v[186:189], v[112:115]
	v_mfma_f32_16x16x32_bf16 v[112:115], v[174:177], v[190:193], v[112:115]
	s_waitcnt lgkmcnt(0)
	v_mfma_f32_16x16x32_bf16 v[116:119], v[142:145], v[186:189], v[116:119]
	v_mfma_f32_16x16x32_bf16 v[116:119], v[166:169], v[190:193], v[116:119]
	s_waitcnt lgkmcnt(3)
	v_mfma_f32_16x16x32_bf16 v[108:111], v[142:145], v[194:197], v[108:111]
	s_waitcnt lgkmcnt(1)
	v_mfma_f32_16x16x32_bf16 v[108:111], v[166:169], v[198:201], v[108:111]
	v_mfma_f32_16x16x32_bf16 v[104:107], v[170:173], v[194:197], v[104:107]
	v_mfma_f32_16x16x32_bf16 v[104:107], v[174:177], v[198:201], v[104:107]
	v_mfma_f32_16x16x32_bf16 v[72:75], v[218:221], v[194:197], v[72:75]
	v_mfma_f32_16x16x32_bf16 v[72:75], v[222:225], v[198:201], v[72:75]
	v_mfma_f32_16x16x32_bf16 v[76:79], v[210:213], v[194:197], v[76:79]
	v_mfma_f32_16x16x32_bf16 v[76:79], v[214:217], v[198:201], v[76:79]
	v_mfma_f32_16x16x32_bf16 v[68:71], v[210:213], v[202:205], v[68:71]
	s_waitcnt lgkmcnt(0)
	v_mfma_f32_16x16x32_bf16 v[68:71], v[214:217], v[206:209], v[68:71]
	v_mfma_f32_16x16x32_bf16 v[64:67], v[218:221], v[202:205], v[64:67]
	v_mfma_f32_16x16x32_bf16 v[64:67], v[222:225], v[206:209], v[64:67]
	v_mfma_f32_16x16x32_bf16 v[96:99], v[170:173], v[202:205], v[96:99]
	v_mfma_f32_16x16x32_bf16 v[96:99], v[174:177], v[206:209], v[96:99]
	v_mfma_f32_16x16x32_bf16 v[100:103], v[142:145], v[202:205], v[100:103]
	v_mfma_f32_16x16x32_bf16 v[100:103], v[166:169], v[206:209], v[100:103]
	s_barrier
	s_cselect_b32 s70, 0, s94
	s_lshl_b64 s[96:97], s[70:71], 1
	s_add_u32 s12, s83, s96
	s_addc_u32 s13, s82, s97
	s_add_u32 s14, s12, 0x58000
	s_mov_b32 m0, s20
	s_nop 0
	global_load_lds_dwordx4 v130, s[12:13]
	s_addc_u32 s15, s13, 0
	s_mov_b32 m0, s21
	s_nop 0
	global_load_lds_dwordx4 v130, s[14:15]
	ds_read_b128 v[178:181], v136 offset:16384
	ds_read_b128 v[182:185], v137 offset:16384
	ds_read_b128 v[186:189], v136 offset:18432
	ds_read_b128 v[190:193], v137 offset:18432
	ds_read_b128 v[194:197], v136 offset:20480
	ds_read_b128 v[198:201], v137 offset:20480
	ds_read_b128 v[202:205], v136 offset:22528
	ds_read_b128 v[206:209], v137 offset:22528
	s_add_u32 s14, s93, s96
	s_addc_u32 s15, s92, s97
	s_add_u32 s92, s14, 0x58000
	s_mov_b32 m0, s19
	s_nop 0
	global_load_lds_dwordx4 v130, s[14:15]
	s_addc_u32 s93, s15, 0
	s_mov_b32 m0, s22
	s_nop 0
	global_load_lds_dwordx4 v130, s[92:93]
	s_add_u32 s83, s83, 0xb0000
	s_addc_u32 s82, s82, 0
	s_add_u32 s92, s83, s96
	s_addc_u32 s93, s82, s97
	s_add_u32 s96, s92, 0x58000
	s_mov_b32 m0, s23
	s_nop 0
	global_load_lds_dwordx4 v130, s[92:93]
	s_addc_u32 s97, s93, 0
	s_mov_b32 m0, s24
	s_nop 0
	global_load_lds_dwordx4 v130, s[96:97]
	s_waitcnt vmcnt(8) lgkmcnt(0)
	s_barrier
	s_waitcnt lgkmcnt(7)
	v_mfma_f32_16x16x32_bf16 v[60:63], v[142:145], v[178:181], v[60:63]
	v_mfma_f32_16x16x32_bf16 v[60:63], v[166:169], v[182:185], v[60:63]
	s_waitcnt lgkmcnt(5)
	v_mfma_f32_16x16x32_bf16 v[56:59], v[170:173], v[178:181], v[56:59]
	v_mfma_f32_16x16x32_bf16 v[56:59], v[174:177], v[182:185], v[56:59]
	s_waitcnt lgkmcnt(3)
	v_mfma_f32_16x16x32_bf16 v[24:27], v[218:221], v[178:181], v[24:27]
	v_mfma_f32_16x16x32_bf16 v[24:27], v[222:225], v[182:185], v[24:27]
	s_waitcnt lgkmcnt(1)
	v_mfma_f32_16x16x32_bf16 v[28:31], v[210:213], v[178:181], v[28:31]
	v_mfma_f32_16x16x32_bf16 v[28:31], v[214:217], v[182:185], v[28:31]
	v_mfma_f32_16x16x32_bf16 v[20:23], v[210:213], v[186:189], v[20:23]
	v_mfma_f32_16x16x32_bf16 v[20:23], v[214:217], v[190:193], v[20:23]
	v_mfma_f32_16x16x32_bf16 v[16:19], v[218:221], v[186:189], v[16:19]
	v_mfma_f32_16x16x32_bf16 v[16:19], v[222:225], v[190:193], v[16:19]
	v_mfma_f32_16x16x32_bf16 v[48:51], v[170:173], v[186:189], v[48:51]
	v_mfma_f32_16x16x32_bf16 v[48:51], v[174:177], v[190:193], v[48:51]
	s_waitcnt lgkmcnt(0)
	v_mfma_f32_16x16x32_bf16 v[52:55], v[142:145], v[186:189], v[52:55]
	v_mfma_f32_16x16x32_bf16 v[52:55], v[166:169], v[190:193], v[52:55]
	v_mfma_f32_16x16x32_bf16 v[44:47], v[142:145], v[194:197], v[44:47]
	v_mfma_f32_16x16x32_bf16 v[44:47], v[166:169], v[198:201], v[44:47]
	v_mfma_f32_16x16x32_bf16 v[40:43], v[170:173], v[194:197], v[40:43]
	v_mfma_f32_16x16x32_bf16 v[40:43], v[174:177], v[198:201], v[40:43]
	v_mfma_f32_16x16x32_bf16 v[8:11], v[218:221], v[194:197], v[8:11]
	v_mfma_f32_16x16x32_bf16 v[8:11], v[222:225], v[198:201], v[8:11]
	v_mfma_f32_16x16x32_bf16 v[12:15], v[210:213], v[194:197], v[12:15]
	v_mfma_f32_16x16x32_bf16 v[12:15], v[214:217], v[198:201], v[12:15]
	v_mfma_f32_16x16x32_bf16 v[4:7], v[210:213], v[202:205], v[4:7]
	v_mfma_f32_16x16x32_bf16 v[4:7], v[214:217], v[206:209], v[4:7]
	v_mfma_f32_16x16x32_bf16 v[0:3], v[218:221], v[202:205], v[0:3]
	v_mfma_f32_16x16x32_bf16 v[0:3], v[222:225], v[206:209], v[0:3]
	v_mfma_f32_16x16x32_bf16 v[32:35], v[170:173], v[202:205], v[32:35]
	v_mfma_f32_16x16x32_bf16 v[32:35], v[174:177], v[206:209], v[32:35]
	v_mfma_f32_16x16x32_bf16 v[36:39], v[142:145], v[202:205], v[36:39]
	v_mfma_f32_16x16x32_bf16 v[36:39], v[166:169], v[206:209], v[36:39]
	s_barrier
	ds_read_b128 v[142:145], v135 offset:32768
	ds_read_b128 v[166:169], v139 offset:32768
	ds_read_b128 v[170:173], v135 offset:34816
	ds_read_b128 v[174:177], v139 offset:34816
	ds_read_b128 v[178:181], v136 offset:32768
	ds_read_b128 v[182:185], v137 offset:32768
	ds_read_b128 v[186:189], v136 offset:34816
	ds_read_b128 v[190:193], v137 offset:34816
	ds_read_b128 v[194:197], v136 offset:36864
	ds_read_b128 v[198:201], v137 offset:36864
	ds_read_b128 v[202:205], v136 offset:38912
	ds_read_b128 v[206:209], v137 offset:38912
	s_add_u32 s92, s14, 0xb0000
	s_addc_u32 s93, s15, 0
	s_add_u32 s96, s14, 0x108000
	s_mov_b32 m0, s25
	s_nop 0
	global_load_lds_dwordx4 v130, s[92:93]
	s_addc_u32 s97, s15, 0
	s_mov_b32 m0, s26
	s_nop 0
	global_load_lds_dwordx4 v130, s[96:97]
	ds_read_b128 v[210:213], v135 offset:49152
	ds_read_b128 v[214:217], v139 offset:49152
	ds_read_b128 v[218:221], v135 offset:51200
	ds_read_b128 v[222:225], v139 offset:51200
	s_waitcnt vmcnt(8) lgkmcnt(0)
	s_barrier
	s_waitcnt lgkmcnt(7)
	v_mfma_f32_16x16x32_bf16 v[124:127], v[142:145], v[178:181], v[124:127]
	v_mfma_f32_16x16x32_bf16 v[124:127], v[166:169], v[182:185], v[124:127]
	s_waitcnt lgkmcnt(5)
	v_mfma_f32_16x16x32_bf16 v[120:123], v[170:173], v[178:181], v[120:123]
	v_mfma_f32_16x16x32_bf16 v[120:123], v[174:177], v[182:185], v[120:123]
	s_waitcnt lgkmcnt(3)
	v_mfma_f32_16x16x32_bf16 v[88:91], v[218:221], v[178:181], v[88:91]
	v_mfma_f32_16x16x32_bf16 v[88:91], v[222:225], v[182:185], v[88:91]
	s_waitcnt lgkmcnt(1)
	v_mfma_f32_16x16x32_bf16 v[92:95], v[210:213], v[178:181], v[92:95]
	v_mfma_f32_16x16x32_bf16 v[92:95], v[214:217], v[182:185], v[92:95]
	v_mfma_f32_16x16x32_bf16 v[84:87], v[210:213], v[186:189], v[84:87]
	v_mfma_f32_16x16x32_bf16 v[84:87], v[214:217], v[190:193], v[84:87]
	v_mfma_f32_16x16x32_bf16 v[80:83], v[218:221], v[186:189], v[80:83]
	v_mfma_f32_16x16x32_bf16 v[80:83], v[222:225], v[190:193], v[80:83]
	v_mfma_f32_16x16x32_bf16 v[112:115], v[170:173], v[186:189], v[112:115]
	v_mfma_f32_16x16x32_bf16 v[112:115], v[174:177], v[190:193], v[112:115]
	s_waitcnt lgkmcnt(0)
	v_mfma_f32_16x16x32_bf16 v[116:119], v[142:145], v[186:189], v[116:119]
	v_mfma_f32_16x16x32_bf16 v[116:119], v[166:169], v[190:193], v[116:119]
	s_waitcnt lgkmcnt(3)
	v_mfma_f32_16x16x32_bf16 v[108:111], v[142:145], v[194:197], v[108:111]
	s_waitcnt lgkmcnt(1)
	v_mfma_f32_16x16x32_bf16 v[108:111], v[166:169], v[198:201], v[108:111]
	v_mfma_f32_16x16x32_bf16 v[104:107], v[170:173], v[194:197], v[104:107]
	v_mfma_f32_16x16x32_bf16 v[104:107], v[174:177], v[198:201], v[104:107]
	v_mfma_f32_16x16x32_bf16 v[72:75], v[218:221], v[194:197], v[72:75]
	v_mfma_f32_16x16x32_bf16 v[72:75], v[222:225], v[198:201], v[72:75]
	v_mfma_f32_16x16x32_bf16 v[76:79], v[210:213], v[194:197], v[76:79]
	v_mfma_f32_16x16x32_bf16 v[76:79], v[214:217], v[198:201], v[76:79]
	v_mfma_f32_16x16x32_bf16 v[68:71], v[210:213], v[202:205], v[68:71]
	s_waitcnt lgkmcnt(0)
	v_mfma_f32_16x16x32_bf16 v[68:71], v[214:217], v[206:209], v[68:71]
	v_mfma_f32_16x16x32_bf16 v[64:67], v[218:221], v[202:205], v[64:67]
	v_mfma_f32_16x16x32_bf16 v[64:67], v[222:225], v[206:209], v[64:67]
	v_mfma_f32_16x16x32_bf16 v[96:99], v[170:173], v[202:205], v[96:99]
	v_mfma_f32_16x16x32_bf16 v[96:99], v[174:177], v[206:209], v[96:99]
	v_mfma_f32_16x16x32_bf16 v[100:103], v[142:145], v[202:205], v[100:103]
	v_mfma_f32_16x16x32_bf16 v[100:103], v[166:169], v[206:209], v[100:103]
	s_barrier
; template <int N, int K, int EPI>
; __device__ void gemm_phase(const u16* __restrict__ A, const u16* __restrict__ Bt, const EpiArgs ea, char* smem, int tid) {
;     ...
;     for (int t = 0; t < nt; t += 2) {
;       const bool lastit = (t == nt - 2);
;       const u16* A2 = lastit ? Abn : Ab;
;       const u16* B2 = lastit ? Bbn : Bb;
;       const int k2 = lastit ? 0 : t + 2;
;       BODY(Ab, t + 1, A2, B2, k2, k2 + 1);
	s_or_b32 s70, s70, 64
	s_add_u32 s92, s12, 0x80
	s_addc_u32 s93, s13, 0
	s_add_u32 s12, s12, 0x58080
	s_mov_b32 m0, s27
	s_nop 0
	global_load_lds_dwordx4 v130, s[92:93]
	s_addc_u32 s13, s13, 0
	s_mov_b32 m0, s28
	s_nop 0
	global_load_lds_dwordx4 v130, s[12:13]
	ds_read_b128 v[178:181], v136 offset:49152
	ds_read_b128 v[182:185], v137 offset:49152
	ds_read_b128 v[186:189], v136 offset:51200
	ds_read_b128 v[190:193], v137 offset:51200
	ds_read_b128 v[194:197], v136 offset:53248
	ds_read_b128 v[198:201], v137 offset:53248
	ds_read_b128 v[202:205], v136 offset:55296
	ds_read_b128 v[206:209], v137 offset:55296
	s_add_u32 s12, s14, 0x80
	s_addc_u32 s13, s15, 0
	s_add_u32 s14, s14, 0x58080
	s_mov_b32 m0, s29
	s_nop 0
	global_load_lds_dwordx4 v130, s[12:13]
	s_addc_u32 s15, s15, 0
	s_mov_b32 m0, s30
	s_nop 0
	global_load_lds_dwordx4 v130, s[14:15]
	s_lshl_b64 s[12:13], s[70:71], 1
	s_add_u32 s12, s83, s12
	s_addc_u32 s13, s82, s13
	s_add_u32 s14, s12, 0x58000
	s_mov_b32 m0, s31
	s_nop 0
	global_load_lds_dwordx4 v130, s[12:13]
	s_addc_u32 s15, s13, 0
	s_mov_b32 m0, s34
	s_nop 0
	global_load_lds_dwordx4 v130, s[14:15]
	s_waitcnt vmcnt(8) lgkmcnt(0)
	s_barrier
	s_waitcnt lgkmcnt(7)
	v_mfma_f32_16x16x32_bf16 v[60:63], v[142:145], v[178:181], v[60:63]
	v_mfma_f32_16x16x32_bf16 v[60:63], v[166:169], v[182:185], v[60:63]
	s_waitcnt lgkmcnt(5)
	v_mfma_f32_16x16x32_bf16 v[56:59], v[170:173], v[178:181], v[56:59]
	v_mfma_f32_16x16x32_bf16 v[56:59], v[174:177], v[182:185], v[56:59]
	s_waitcnt lgkmcnt(3)
	v_mfma_f32_16x16x32_bf16 v[24:27], v[218:221], v[178:181], v[24:27]
	v_mfma_f32_16x16x32_bf16 v[24:27], v[222:225], v[182:185], v[24:27]
	s_waitcnt lgkmcnt(1)
	v_mfma_f32_16x16x32_bf16 v[28:31], v[210:213], v[178:181], v[28:31]
	v_mfma_f32_16x16x32_bf16 v[28:31], v[214:217], v[182:185], v[28:31]
	v_mfma_f32_16x16x32_bf16 v[20:23], v[210:213], v[186:189], v[20:23]
	v_mfma_f32_16x16x32_bf16 v[20:23], v[214:217], v[190:193], v[20:23]
	v_mfma_f32_16x16x32_bf16 v[16:19], v[218:221], v[186:189], v[16:19]
	v_mfma_f32_16x16x32_bf16 v[16:19], v[222:225], v[190:193], v[16:19]
	v_mfma_f32_16x16x32_bf16 v[48:51], v[170:173], v[186:189], v[48:51]
	v_mfma_f32_16x16x32_bf16 v[48:51], v[174:177], v[190:193], v[48:51]
	s_waitcnt lgkmcnt(0)
	v_mfma_f32_16x16x32_bf16 v[52:55], v[142:145], v[186:189], v[52:55]
	v_mfma_f32_16x16x32_bf16 v[52:55], v[166:169], v[190:193], v[52:55]
	v_mfma_f32_16x16x32_bf16 v[44:47], v[142:145], v[194:197], v[44:47]
	v_mfma_f32_16x16x32_bf16 v[44:47], v[166:169], v[198:201], v[44:47]
	v_mfma_f32_16x16x32_bf16 v[40:43], v[170:173], v[194:197], v[40:43]
	v_mfma_f32_16x16x32_bf16 v[40:43], v[174:177], v[198:201], v[40:43]
	v_mfma_f32_16x16x32_bf16 v[8:11], v[218:221], v[194:197], v[8:11]
	v_mfma_f32_16x16x32_bf16 v[8:11], v[222:225], v[198:201], v[8:11]
	v_mfma_f32_16x16x32_bf16 v[12:15], v[210:213], v[194:197], v[12:15]
	v_mfma_f32_16x16x32_bf16 v[12:15], v[214:217], v[198:201], v[12:15]
	v_mfma_f32_16x16x32_bf16 v[4:7], v[210:213], v[202:205], v[4:7]
	v_mfma_f32_16x16x32_bf16 v[4:7], v[214:217], v[206:209], v[4:7]
	v_mfma_f32_16x16x32_bf16 v[0:3], v[218:221], v[202:205], v[0:3]
	v_mfma_f32_16x16x32_bf16 v[0:3], v[222:225], v[206:209], v[0:3]
	v_mfma_f32_16x16x32_bf16 v[32:35], v[170:173], v[202:205], v[32:35]
	v_mfma_f32_16x16x32_bf16 v[32:35], v[174:177], v[206:209], v[32:35]
	v_mfma_f32_16x16x32_bf16 v[36:39], v[142:145], v[202:205], v[36:39]
	v_mfma_f32_16x16x32_bf16 v[36:39], v[166:169], v[206:209], v[36:39]
	s_add_i32 s89, s89, 2
	s_addk_i32 s94, 0x80
	s_add_u32 s10, s10, 0x100
	s_addc_u32 s11, s11, 0
	s_cmp_gt_u32 s89, 41
	s_barrier
	s_cbranch_scc0 .LBB0_220
; #define WAIT_V(n) asm volatile("s_waitcnt vmcnt(" #n ")" ::: "memory")
; #define BAR __builtin_amdgcn_s_barrier()
; template <int N, int K, int EPI>
; __device__ void gemm_phase(const u16* __restrict__ A, const u16* __restrict__ Bt, const EpiArgs ea, char* smem, int tid) {
;     ...
;       } else if constexpr (EPI == EPI_F) {
;         u16* f = ea.o0;
; #pragma unroll
;         for (int ai = 0; ai < 2; ++ai)
; #pragma unroll
;           for (int bj = 0; bj < 2; ++bj)
; #pragma unroll
;             for (int m = 0; m < 4; ++m) {
;               const int row = brow + ai * HALF + wr * 64 + m * 16 + fr_e;
;               const int col = pn * BM + bj * HALF + wc * 32 + fq_e * 8;
;               const f32x4 v0 = acc[ai][bj][m][0], v1 = acc[ai][bj][m][1];
;               u32x4 o = {pk_bf16(v0[0], v0[1]), pk_bf16(v0[2], v0[3]), pk_bf16(v1[0], v1[1]), pk_bf16(v1[2], v1[3])};
;               *(u32x4*)(f + (size_t)row * N + col) = o;
;             }
;     ...
;     if (!has_next) break;
; #pragma unroll
;     for (int ai = 0; ai < 2; ++ai)
; #pragma unroll
;       for (int bj = 0; bj < 2; ++bj)
; #pragma unroll
;         for (int m = 0; m < 4; ++m)
; #pragma unroll
;           for (int n = 0; n < 2; ++n) acc[ai][bj][m][n] = f32x4{0.f, 0.f, 0.f, 0.f};
;     v = vn; pm = pmn; pn = pnn; Ab = Abn; Bb = Bbn;
;   }
;   WAIT_V(0);
;   if (wr == 0) BAR;
	s_lshl_b32 s6, s88, 8
	v_mov_b32_e32 v128, v131
	v_mov_b32_e32 v129, v132
	s_add_i32 s6, s6, s35
	v_cvt_pk_bf16_f32 v124, v124, v125
	v_cvt_pk_bf16_f32 v125, v126, v127
	v_cvt_pk_bf16_f32 v126, v120, v121
	v_cvt_pk_bf16_f32 v127, v122, v123
	v_cvt_pk_bf16_f32 v116, v116, v117
	s_nop 0
	v_add_u32_e32 v142, s6, v128
	s_lshl_b32 s6, s73, 8
	s_or_b32 s6, s6, s42
	v_lshl_add_u32 v144, v129, 3, s6
	v_ashrrev_i32_e32 v145, 31, v144
	v_ashrrev_i32_e32 v143, 31, v142
	v_lshl_add_u64 v[128:129], v[144:145], 1, s[64:65]
	v_lshlrev_b64 v[120:121], 11, v[142:143]
	v_lshl_add_u64 v[122:123], v[128:129], 0, v[120:121]
	global_store_dwordx4 v[122:123], v[124:127], off
	v_add_u32_e32 v122, 16, v142
	v_ashrrev_i32_e32 v123, 31, v122
	v_cvt_pk_bf16_f32 v117, v118, v119
	v_cvt_pk_bf16_f32 v118, v112, v113
	v_lshlrev_b64 v[112:113], 11, v[122:123]
	v_cvt_pk_bf16_f32 v119, v114, v115
	v_lshl_add_u64 v[114:115], v[128:129], 0, v[112:113]
	global_store_dwordx4 v[114:115], v[116:119], off
	v_add_u32_e32 v114, 32, v142
	v_ashrrev_i32_e32 v115, 31, v114
	v_cvt_pk_bf16_f32 v108, v108, v109
	v_cvt_pk_bf16_f32 v109, v110, v111
	v_cvt_pk_bf16_f32 v110, v104, v105
	v_lshlrev_b64 v[104:105], 11, v[114:115]
	v_cvt_pk_bf16_f32 v111, v106, v107
	v_lshl_add_u64 v[106:107], v[128:129], 0, v[104:105]
	global_store_dwordx4 v[106:107], v[108:111], off
	v_add_u32_e32 v106, 48, v142
	v_ashrrev_i32_e32 v107, 31, v106
	v_cvt_pk_bf16_f32 v100, v100, v101
	v_cvt_pk_bf16_f32 v101, v102, v103
	v_cvt_pk_bf16_f32 v102, v96, v97
	v_lshlrev_b64 v[96:97], 11, v[106:107]
	v_cvt_pk_bf16_f32 v103, v98, v99
	v_lshl_add_u64 v[98:99], v[128:129], 0, v[96:97]
	global_store_dwordx4 v[98:99], v[100:103], off
	v_add_u32_e32 v98, 0x80, v144
	v_ashrrev_i32_e32 v99, 31, v98
	v_lshl_add_u64 v[98:99], v[98:99], 1, s[64:65]
	v_cvt_pk_bf16_f32 v68, v68, v69
	v_cvt_pk_bf16_f32 v69, v70, v71
	v_cvt_pk_bf16_f32 v70, v64, v65
	v_lshl_add_u64 v[64:65], v[98:99], 0, v[96:97]
	v_cvt_pk_bf16_f32 v71, v66, v67
	global_store_dwordx4 v[64:65], v[68:71], off
	v_add_u32_e32 v64, 0x80, v142
	v_ashrrev_i32_e32 v65, 31, v64
	v_cvt_pk_bf16_f32 v60, v60, v61
	v_cvt_pk_bf16_f32 v61, v62, v63
	v_cvt_pk_bf16_f32 v62, v56, v57
	v_lshlrev_b64 v[56:57], 11, v[64:65]
	v_cvt_pk_bf16_f32 v92, v92, v93
	v_cvt_pk_bf16_f32 v93, v94, v95
	v_cvt_pk_bf16_f32 v94, v88, v89
	v_lshl_add_u64 v[88:89], v[98:99], 0, v[120:121]
	v_cvt_pk_bf16_f32 v84, v84, v85
	v_cvt_pk_bf16_f32 v85, v86, v87
	v_cvt_pk_bf16_f32 v86, v80, v81
	v_lshl_add_u64 v[80:81], v[98:99], 0, v[112:113]
	v_cvt_pk_bf16_f32 v76, v76, v77
	v_cvt_pk_bf16_f32 v77, v78, v79
	v_cvt_pk_bf16_f32 v78, v72, v73
	v_lshl_add_u64 v[72:73], v[98:99], 0, v[104:105]
	v_cvt_pk_bf16_f32 v63, v58, v59
	v_lshl_add_u64 v[58:59], v[128:129], 0, v[56:57]
	v_cvt_pk_bf16_f32 v95, v90, v91
	global_store_dwordx4 v[88:89], v[92:95], off
	v_cvt_pk_bf16_f32 v87, v82, v83
	global_store_dwordx4 v[80:81], v[84:87], off
	v_cvt_pk_bf16_f32 v79, v74, v75
	global_store_dwordx4 v[72:73], v[76:79], off
	global_store_dwordx4 v[58:59], v[60:63], off
	v_add_u32_e32 v58, 0x90, v142
	v_ashrrev_i32_e32 v59, 31, v58
	v_cvt_pk_bf16_f32 v52, v52, v53
	v_cvt_pk_bf16_f32 v53, v54, v55
	v_cvt_pk_bf16_f32 v54, v48, v49
	v_lshlrev_b64 v[48:49], 11, v[58:59]
	v_cvt_pk_bf16_f32 v55, v50, v51
	v_lshl_add_u64 v[50:51], v[128:129], 0, v[48:49]
	global_store_dwordx4 v[50:51], v[52:55], off
	v_add_u32_e32 v50, 0xa0, v142
	v_ashrrev_i32_e32 v51, 31, v50
	v_cvt_pk_bf16_f32 v44, v44, v45
	v_cvt_pk_bf16_f32 v45, v46, v47
	v_cvt_pk_bf16_f32 v46, v40, v41
	v_lshlrev_b64 v[40:41], 11, v[50:51]
	v_cvt_pk_bf16_f32 v47, v42, v43
	v_lshl_add_u64 v[42:43], v[128:129], 0, v[40:41]
	global_store_dwordx4 v[42:43], v[44:47], off
	v_add_u32_e32 v42, 0xb0, v142
	v_ashrrev_i32_e32 v43, 31, v42
	v_cvt_pk_bf16_f32 v36, v36, v37
	v_cvt_pk_bf16_f32 v37, v38, v39
	v_cvt_pk_bf16_f32 v38, v32, v33
	v_lshlrev_b64 v[32:33], 11, v[42:43]
	v_cvt_pk_bf16_f32 v39, v34, v35
	v_lshl_add_u64 v[34:35], v[128:129], 0, v[32:33]
	v_cvt_pk_bf16_f32 v28, v28, v29
	v_cvt_pk_bf16_f32 v29, v30, v31
	v_cvt_pk_bf16_f32 v30, v24, v25
	v_lshl_add_u64 v[24:25], v[98:99], 0, v[56:57]
	v_cvt_pk_bf16_f32 v20, v20, v21
	v_cvt_pk_bf16_f32 v21, v22, v23
	v_cvt_pk_bf16_f32 v22, v16, v17
	v_lshl_add_u64 v[16:17], v[98:99], 0, v[48:49]
	v_cvt_pk_bf16_f32 v12, v12, v13
	v_cvt_pk_bf16_f32 v13, v14, v15
	v_cvt_pk_bf16_f32 v14, v8, v9
	v_lshl_add_u64 v[8:9], v[98:99], 0, v[40:41]
	v_cvt_pk_bf16_f32 v4, v4, v5
	v_cvt_pk_bf16_f32 v5, v6, v7
	v_cvt_pk_bf16_f32 v6, v0, v1
	v_lshl_add_u64 v[0:1], v[98:99], 0, v[32:33]
	s_and_b64 vcc, exec, s[0:1]
	s_mov_b32 s88, s67
	s_mov_b32 s73, s72
	s_mov_b64 s[8:9], s[4:5]
	s_mov_b64 s[6:7], s[2:3]
	global_store_dwordx4 v[34:35], v[36:39], off
	v_cvt_pk_bf16_f32 v31, v26, v27
	global_store_dwordx4 v[24:25], v[28:31], off
	v_cvt_pk_bf16_f32 v23, v18, v19
	global_store_dwordx4 v[16:17], v[20:23], off
	v_cvt_pk_bf16_f32 v15, v10, v11
	global_store_dwordx4 v[8:9], v[12:15], off
	v_cvt_pk_bf16_f32 v7, v2, v3
	global_store_dwordx4 v[0:1], v[4:7], off
	s_cbranch_vccz .LBB0_217
	s_setprio 0
	s_waitcnt vmcnt(0)
	v_readlane_b32 s34, v226, 32
	v_readlane_b32 s36, v226, 30
	s_cmpk_gt_u32 s18, 0xff
	s_movk_i32 s27, 0x7fff
	s_mov_b32 s28, 0x800000
	s_mov_b32 s29, 0xa000000
	s_mov_b32 s30, 0x41000
	v_readlane_b32 s35, v226, 33
	v_readlane_b32 s37, v226, 31
	s_cbranch_scc1 .LBB0_224
	s_barrier

.LBB0_236:
	ds_read_b128 v[142:145], v135
	ds_read_b128 v[166:169], v139
	ds_read_b128 v[170:173], v135 offset:2048
	ds_read_b128 v[174:177], v139 offset:2048
	s_add_u32 s16, s14, 0x40080
	s_addc_u32 s17, s15, 0
	s_add_u32 s18, s14, 0x60080
	s_addc_u32 s19, s15, 0
	s_cmp_eq_u32 s3, 12
	s_cselect_b32 s82, s9, s13
	s_cselect_b32 s83, s8, s12
	s_cselect_b32 s92, s7, s11
	s_cselect_b32 s93, s6, s10
	s_nop 0
	ds_read_b128 v[178:181], v136
	ds_read_b128 v[182:185], v137
	ds_read_b128 v[186:189], v136 offset:2048
	ds_read_b128 v[190:193], v137 offset:2048
	ds_read_b128 v[194:197], v136 offset:4096
	ds_read_b128 v[198:201], v137 offset:4096
	ds_read_b128 v[202:205], v136 offset:6144
	ds_read_b128 v[206:209], v137 offset:6144
	s_mov_b32 m0, s64
	s_nop 0
	global_load_lds_dwordx4 v130, s[16:17]
	s_nop 0
	s_mov_b32 m0, s65
	s_nop 0
	global_load_lds_dwordx4 v130, s[18:19]
	ds_read_b128 v[210:213], v135 offset:16384
	ds_read_b128 v[214:217], v139 offset:16384
	ds_read_b128 v[218:221], v135 offset:18432
	ds_read_b128 v[222:225], v139 offset:18432
	s_waitcnt vmcnt(8) lgkmcnt(0)
	s_barrier
	s_waitcnt lgkmcnt(7)
	v_mfma_f32_16x16x32_bf16 v[124:127], v[142:145], v[178:181], v[124:127]
	v_mfma_f32_16x16x32_bf16 v[124:127], v[166:169], v[182:185], v[124:127]
	s_waitcnt lgkmcnt(5)
	v_mfma_f32_16x16x32_bf16 v[116:119], v[170:173], v[178:181], v[116:119]
	v_mfma_f32_16x16x32_bf16 v[116:119], v[174:177], v[182:185], v[116:119]
	s_waitcnt lgkmcnt(3)
	v_mfma_f32_16x16x32_bf16 v[112:115], v[218:221], v[178:181], v[112:115]
	v_mfma_f32_16x16x32_bf16 v[112:115], v[222:225], v[182:185], v[112:115]
	s_waitcnt lgkmcnt(1)
	v_mfma_f32_16x16x32_bf16 v[120:123], v[210:213], v[178:181], v[120:123]
	v_mfma_f32_16x16x32_bf16 v[120:123], v[214:217], v[182:185], v[120:123]
	v_mfma_f32_16x16x32_bf16 v[104:107], v[210:213], v[186:189], v[104:107]
	v_mfma_f32_16x16x32_bf16 v[104:107], v[214:217], v[190:193], v[104:107]
	v_mfma_f32_16x16x32_bf16 v[96:99], v[218:221], v[186:189], v[96:99]
	v_mfma_f32_16x16x32_bf16 v[96:99], v[222:225], v[190:193], v[96:99]
	v_mfma_f32_16x16x32_bf16 v[100:103], v[170:173], v[186:189], v[100:103]
	v_mfma_f32_16x16x32_bf16 v[100:103], v[174:177], v[190:193], v[100:103]
	s_waitcnt lgkmcnt(0)
	v_mfma_f32_16x16x32_bf16 v[108:111], v[142:145], v[186:189], v[108:111]
	v_mfma_f32_16x16x32_bf16 v[108:111], v[166:169], v[190:193], v[108:111]
	s_waitcnt lgkmcnt(3)
	v_mfma_f32_16x16x32_bf16 v[92:95], v[142:145], v[194:197], v[92:95]
	s_waitcnt lgkmcnt(1)
	v_mfma_f32_16x16x32_bf16 v[92:95], v[166:169], v[198:201], v[92:95]
	v_mfma_f32_16x16x32_bf16 v[84:87], v[170:173], v[194:197], v[84:87]
	v_mfma_f32_16x16x32_bf16 v[84:87], v[174:177], v[198:201], v[84:87]
	v_mfma_f32_16x16x32_bf16 v[80:83], v[218:221], v[194:197], v[80:83]
	v_mfma_f32_16x16x32_bf16 v[80:83], v[222:225], v[198:201], v[80:83]
	v_mfma_f32_16x16x32_bf16 v[88:91], v[210:213], v[194:197], v[88:91]
	v_mfma_f32_16x16x32_bf16 v[88:91], v[214:217], v[198:201], v[88:91]
	v_mfma_f32_16x16x32_bf16 v[72:75], v[210:213], v[202:205], v[72:75]
	s_waitcnt lgkmcnt(0)
	v_mfma_f32_16x16x32_bf16 v[72:75], v[214:217], v[206:209], v[72:75]
	v_mfma_f32_16x16x32_bf16 v[64:67], v[218:221], v[202:205], v[64:67]
	v_mfma_f32_16x16x32_bf16 v[64:67], v[222:225], v[206:209], v[64:67]
	v_mfma_f32_16x16x32_bf16 v[68:71], v[170:173], v[202:205], v[68:71]
	v_mfma_f32_16x16x32_bf16 v[68:71], v[174:177], v[206:209], v[68:71]
	v_mfma_f32_16x16x32_bf16 v[76:79], v[142:145], v[202:205], v[76:79]
	v_mfma_f32_16x16x32_bf16 v[76:79], v[166:169], v[206:209], v[76:79]
	s_barrier
	s_cselect_b32 s70, 0, s5
	s_lshl_b64 s[88:89], s[70:71], 1
	s_add_u32 s16, s83, s88
	s_addc_u32 s17, s82, s89
	s_add_u32 s18, s16, 0x20000
	s_mov_b32 m0, s24
	s_nop 0
	global_load_lds_dwordx4 v130, s[16:17]
	s_addc_u32 s19, s17, 0
	s_mov_b32 m0, s25
	s_nop 0
	global_load_lds_dwordx4 v130, s[18:19]
	ds_read_b128 v[178:181], v136 offset:16384
	ds_read_b128 v[182:185], v137 offset:16384
	ds_read_b128 v[186:189], v136 offset:18432
	ds_read_b128 v[190:193], v137 offset:18432
	ds_read_b128 v[194:197], v136 offset:20480
	ds_read_b128 v[198:201], v137 offset:20480
	ds_read_b128 v[202:205], v136 offset:22528
	ds_read_b128 v[206:209], v137 offset:22528
	s_add_u32 s18, s93, s88
	s_addc_u32 s19, s92, s89
	s_add_u32 s94, s18, 0x20000
	s_mov_b32 m0, s23
	s_nop 0
	global_load_lds_dwordx4 v130, s[18:19]
	s_addc_u32 s95, s19, 0
	s_mov_b32 m0, s26
	s_nop 0
	global_load_lds_dwordx4 v130, s[94:95]
	s_add_u32 s83, s83, 0x40000
	s_addc_u32 s82, s82, 0
	s_add_u32 s88, s83, s88
	s_addc_u32 s89, s82, s89
	s_add_u32 s94, s88, 0x20000
	s_mov_b32 m0, s27
	s_nop 0
	global_load_lds_dwordx4 v130, s[88:89]
	s_addc_u32 s95, s89, 0
	s_mov_b32 m0, s28
	s_nop 0
	global_load_lds_dwordx4 v130, s[94:95]
	s_waitcnt vmcnt(8) lgkmcnt(0)
	s_barrier
	s_waitcnt lgkmcnt(7)
	v_mfma_f32_16x16x32_bf16 v[60:63], v[142:145], v[178:181], v[60:63]
	v_mfma_f32_16x16x32_bf16 v[60:63], v[166:169], v[182:185], v[60:63]
	s_waitcnt lgkmcnt(5)
	v_mfma_f32_16x16x32_bf16 v[52:55], v[170:173], v[178:181], v[52:55]
	v_mfma_f32_16x16x32_bf16 v[52:55], v[174:177], v[182:185], v[52:55]
	s_waitcnt lgkmcnt(3)
	v_mfma_f32_16x16x32_bf16 v[48:51], v[218:221], v[178:181], v[48:51]
	v_mfma_f32_16x16x32_bf16 v[48:51], v[222:225], v[182:185], v[48:51]
	s_waitcnt lgkmcnt(1)
	v_mfma_f32_16x16x32_bf16 v[56:59], v[210:213], v[178:181], v[56:59]
	v_mfma_f32_16x16x32_bf16 v[56:59], v[214:217], v[182:185], v[56:59]
	v_mfma_f32_16x16x32_bf16 v[40:43], v[210:213], v[186:189], v[40:43]
	v_mfma_f32_16x16x32_bf16 v[40:43], v[214:217], v[190:193], v[40:43]
	v_mfma_f32_16x16x32_bf16 v[32:35], v[218:221], v[186:189], v[32:35]
	v_mfma_f32_16x16x32_bf16 v[32:35], v[222:225], v[190:193], v[32:35]
	v_mfma_f32_16x16x32_bf16 v[36:39], v[170:173], v[186:189], v[36:39]
	v_mfma_f32_16x16x32_bf16 v[36:39], v[174:177], v[190:193], v[36:39]
	s_waitcnt lgkmcnt(0)
	v_mfma_f32_16x16x32_bf16 v[44:47], v[142:145], v[186:189], v[44:47]
	v_mfma_f32_16x16x32_bf16 v[44:47], v[166:169], v[190:193], v[44:47]
	v_mfma_f32_16x16x32_bf16 v[28:31], v[142:145], v[194:197], v[28:31]
	v_mfma_f32_16x16x32_bf16 v[28:31], v[166:169], v[198:201], v[28:31]
	v_mfma_f32_16x16x32_bf16 v[20:23], v[170:173], v[194:197], v[20:23]
	v_mfma_f32_16x16x32_bf16 v[20:23], v[174:177], v[198:201], v[20:23]
	v_mfma_f32_16x16x32_bf16 v[16:19], v[218:221], v[194:197], v[16:19]
	v_mfma_f32_16x16x32_bf16 v[16:19], v[222:225], v[198:201], v[16:19]
	v_mfma_f32_16x16x32_bf16 v[24:27], v[210:213], v[194:197], v[24:27]
	v_mfma_f32_16x16x32_bf16 v[24:27], v[214:217], v[198:201], v[24:27]
	v_mfma_f32_16x16x32_bf16 v[8:11], v[210:213], v[202:205], v[8:11]
	v_mfma_f32_16x16x32_bf16 v[8:11], v[214:217], v[206:209], v[8:11]
	v_mfma_f32_16x16x32_bf16 v[0:3], v[218:221], v[202:205], v[0:3]
	v_mfma_f32_16x16x32_bf16 v[0:3], v[222:225], v[206:209], v[0:3]
	v_mfma_f32_16x16x32_bf16 v[4:7], v[170:173], v[202:205], v[4:7]
	v_mfma_f32_16x16x32_bf16 v[4:7], v[174:177], v[206:209], v[4:7]
	v_mfma_f32_16x16x32_bf16 v[12:15], v[142:145], v[202:205], v[12:15]
	v_mfma_f32_16x16x32_bf16 v[12:15], v[166:169], v[206:209], v[12:15]
	s_barrier
	ds_read_b128 v[142:145], v135 offset:32768
	ds_read_b128 v[166:169], v139 offset:32768
	ds_read_b128 v[170:173], v135 offset:34816
	ds_read_b128 v[174:177], v139 offset:34816
	ds_read_b128 v[178:181], v136 offset:32768
	ds_read_b128 v[182:185], v137 offset:32768
	ds_read_b128 v[186:189], v136 offset:34816
	ds_read_b128 v[190:193], v137 offset:34816
	ds_read_b128 v[194:197], v136 offset:36864
	ds_read_b128 v[198:201], v137 offset:36864
	ds_read_b128 v[202:205], v136 offset:38912
	ds_read_b128 v[206:209], v137 offset:38912
	s_add_u32 s88, s18, 0x40000
	s_addc_u32 s89, s19, 0
	s_add_u32 s94, s18, 0x60000
	s_mov_b32 m0, s29
	s_nop 0
	global_load_lds_dwordx4 v130, s[88:89]
	s_addc_u32 s95, s19, 0
	s_mov_b32 m0, s30
	s_nop 0
	global_load_lds_dwordx4 v130, s[94:95]
	ds_read_b128 v[210:213], v135 offset:49152
	ds_read_b128 v[214:217], v139 offset:49152
	ds_read_b128 v[218:221], v135 offset:51200
	ds_read_b128 v[222:225], v139 offset:51200
	s_waitcnt vmcnt(8) lgkmcnt(0)
	s_barrier
	s_waitcnt lgkmcnt(7)
	v_mfma_f32_16x16x32_bf16 v[124:127], v[142:145], v[178:181], v[124:127]
	v_mfma_f32_16x16x32_bf16 v[124:127], v[166:169], v[182:185], v[124:127]
	s_waitcnt lgkmcnt(5)
	v_mfma_f32_16x16x32_bf16 v[116:119], v[170:173], v[178:181], v[116:119]
	v_mfma_f32_16x16x32_bf16 v[116:119], v[174:177], v[182:185], v[116:119]
	s_waitcnt lgkmcnt(3)
	v_mfma_f32_16x16x32_bf16 v[112:115], v[218:221], v[178:181], v[112:115]
	v_mfma_f32_16x16x32_bf16 v[112:115], v[222:225], v[182:185], v[112:115]
	s_waitcnt lgkmcnt(1)
	v_mfma_f32_16x16x32_bf16 v[120:123], v[210:213], v[178:181], v[120:123]
	v_mfma_f32_16x16x32_bf16 v[120:123], v[214:217], v[182:185], v[120:123]
	v_mfma_f32_16x16x32_bf16 v[104:107], v[210:213], v[186:189], v[104:107]
	v_mfma_f32_16x16x32_bf16 v[104:107], v[214:217], v[190:193], v[104:107]
	v_mfma_f32_16x16x32_bf16 v[96:99], v[218:221], v[186:189], v[96:99]
	v_mfma_f32_16x16x32_bf16 v[96:99], v[222:225], v[190:193], v[96:99]
	v_mfma_f32_16x16x32_bf16 v[100:103], v[170:173], v[186:189], v[100:103]
	v_mfma_f32_16x16x32_bf16 v[100:103], v[174:177], v[190:193], v[100:103]
	s_waitcnt lgkmcnt(0)
	v_mfma_f32_16x16x32_bf16 v[108:111], v[142:145], v[186:189], v[108:111]
	v_mfma_f32_16x16x32_bf16 v[108:111], v[166:169], v[190:193], v[108:111]
	s_waitcnt lgkmcnt(3)
	v_mfma_f32_16x16x32_bf16 v[92:95], v[142:145], v[194:197], v[92:95]
	s_waitcnt lgkmcnt(1)
	v_mfma_f32_16x16x32_bf16 v[92:95], v[166:169], v[198:201], v[92:95]
	v_mfma_f32_16x16x32_bf16 v[84:87], v[170:173], v[194:197], v[84:87]
	v_mfma_f32_16x16x32_bf16 v[84:87], v[174:177], v[198:201], v[84:87]
	v_mfma_f32_16x16x32_bf16 v[80:83], v[218:221], v[194:197], v[80:83]
	v_mfma_f32_16x16x32_bf16 v[80:83], v[222:225], v[198:201], v[80:83]
	v_mfma_f32_16x16x32_bf16 v[88:91], v[210:213], v[194:197], v[88:91]
	v_mfma_f32_16x16x32_bf16 v[88:91], v[214:217], v[198:201], v[88:91]
	v_mfma_f32_16x16x32_bf16 v[72:75], v[210:213], v[202:205], v[72:75]
	s_waitcnt lgkmcnt(0)
	v_mfma_f32_16x16x32_bf16 v[72:75], v[214:217], v[206:209], v[72:75]
	v_mfma_f32_16x16x32_bf16 v[64:67], v[218:221], v[202:205], v[64:67]
	v_mfma_f32_16x16x32_bf16 v[64:67], v[222:225], v[206:209], v[64:67]
	v_mfma_f32_16x16x32_bf16 v[68:71], v[170:173], v[202:205], v[68:71]
	v_mfma_f32_16x16x32_bf16 v[68:71], v[174:177], v[206:209], v[68:71]
	v_mfma_f32_16x16x32_bf16 v[76:79], v[142:145], v[202:205], v[76:79]
	v_mfma_f32_16x16x32_bf16 v[76:79], v[166:169], v[206:209], v[76:79]
	s_barrier
; template <int N, int K, int EPI>
; __device__ void gemm_phase(const u16* __restrict__ A, const u16* __restrict__ Bt, const EpiArgs ea, char* smem, int tid) {
;     ...
;       if constexpr (EPI == EPI_SWIGLU) {
;         u16* h = ea.o0;
; #pragma unroll
;         for (int ai = 0; ai < 2; ++ai)
; #pragma unroll
;           for (int m = 0; m < 4; ++m) {
;             const int row = brow + ai * HALF + wr * 64 + m * 16 + fr_e;
;             const int col = pn * 128 + wc * 32 + fq_e * 8;
;             u32x4 o;
; #pragma unroll
;             for (int n = 0; n < 2; ++n) {
;               const f32x4 t4 = acc[ai][0][m][n], u4 = acc[ai][1][m][n];
;               f32x2 tl = {t4[0], t4[1]}, th = {t4[2], t4[3]}, ul = {u4[0], u4[1]}, uh = {u4[2], u4[3]};
;               f32x2 el = {__builtin_amdgcn_exp2f(-t4[0]), __builtin_amdgcn_exp2f(-t4[1])};
;               f32x2 eh = {__builtin_amdgcn_exp2f(-t4[2]), __builtin_amdgcn_exp2f(-t4[3])};
;               el = el + 1.f; eh = eh + 1.f;
;               f32x2 rl = {__builtin_amdgcn_rcpf(el[0]), __builtin_amdgcn_rcpf(el[1])};
;               f32x2 rh = {__builtin_amdgcn_rcpf(eh[0]), __builtin_amdgcn_rcpf(eh[1])};
;               const f32x2 hl = tl * ul * rl, hh2 = th * uh * rh;
;               o[2 * n] = pk_bf16(hl[0], hl[1]); o[2 * n + 1] = pk_bf16(hh2[0], hh2[1]);
;             }
;             *(u32x4*)(h + (size_t)row * FF + col) = o;
	s_or_b32 s70, s70, 64
	s_add_u32 s88, s16, 0x80
	s_addc_u32 s89, s17, 0
	s_add_u32 s16, s16, 0x20080
	s_mov_b32 m0, s31
	s_nop 0
	global_load_lds_dwordx4 v130, s[88:89]
	s_addc_u32 s17, s17, 0
	s_mov_b32 m0, s34
	s_nop 0
	global_load_lds_dwordx4 v130, s[16:17]
	ds_read_b128 v[178:181], v136 offset:49152
	ds_read_b128 v[182:185], v137 offset:49152
	ds_read_b128 v[186:189], v136 offset:51200
	ds_read_b128 v[190:193], v137 offset:51200
	ds_read_b128 v[194:197], v136 offset:53248
	ds_read_b128 v[198:201], v137 offset:53248
	ds_read_b128 v[202:205], v136 offset:55296
	ds_read_b128 v[206:209], v137 offset:55296
	s_add_u32 s16, s18, 0x80
	s_addc_u32 s17, s19, 0
	s_add_u32 s18, s18, 0x20080
	s_mov_b32 m0, s35
	s_nop 0
	global_load_lds_dwordx4 v130, s[16:17]
	s_addc_u32 s19, s19, 0
	s_mov_b32 m0, s36
	s_nop 0
	global_load_lds_dwordx4 v130, s[18:19]
	s_lshl_b64 s[16:17], s[70:71], 1
	s_add_u32 s16, s83, s16
	s_addc_u32 s17, s82, s17
	s_add_u32 s18, s16, 0x20000
	s_mov_b32 m0, s37
	s_nop 0
	global_load_lds_dwordx4 v130, s[16:17]
	s_addc_u32 s19, s17, 0
	s_mov_b32 m0, s42
	s_nop 0
	global_load_lds_dwordx4 v130, s[18:19]
	s_waitcnt vmcnt(8) lgkmcnt(0)
	s_barrier
	s_waitcnt lgkmcnt(7)
	v_mfma_f32_16x16x32_bf16 v[60:63], v[142:145], v[178:181], v[60:63]
	v_mfma_f32_16x16x32_bf16 v[60:63], v[166:169], v[182:185], v[60:63]
	s_waitcnt lgkmcnt(5)
	v_mfma_f32_16x16x32_bf16 v[52:55], v[170:173], v[178:181], v[52:55]
	v_mfma_f32_16x16x32_bf16 v[52:55], v[174:177], v[182:185], v[52:55]
	s_waitcnt lgkmcnt(3)
	v_mfma_f32_16x16x32_bf16 v[48:51], v[218:221], v[178:181], v[48:51]
	v_mfma_f32_16x16x32_bf16 v[48:51], v[222:225], v[182:185], v[48:51]
	s_waitcnt lgkmcnt(1)
	v_mfma_f32_16x16x32_bf16 v[56:59], v[210:213], v[178:181], v[56:59]
	v_mfma_f32_16x16x32_bf16 v[56:59], v[214:217], v[182:185], v[56:59]
	v_mfma_f32_16x16x32_bf16 v[40:43], v[210:213], v[186:189], v[40:43]
	v_mfma_f32_16x16x32_bf16 v[40:43], v[214:217], v[190:193], v[40:43]
	v_mfma_f32_16x16x32_bf16 v[32:35], v[218:221], v[186:189], v[32:35]
	v_mfma_f32_16x16x32_bf16 v[32:35], v[222:225], v[190:193], v[32:35]
	v_mfma_f32_16x16x32_bf16 v[36:39], v[170:173], v[186:189], v[36:39]
	v_mfma_f32_16x16x32_bf16 v[36:39], v[174:177], v[190:193], v[36:39]
	s_waitcnt lgkmcnt(0)
	v_mfma_f32_16x16x32_bf16 v[44:47], v[142:145], v[186:189], v[44:47]
	v_mfma_f32_16x16x32_bf16 v[44:47], v[166:169], v[190:193], v[44:47]
	v_mfma_f32_16x16x32_bf16 v[28:31], v[142:145], v[194:197], v[28:31]
	v_mfma_f32_16x16x32_bf16 v[28:31], v[166:169], v[198:201], v[28:31]
	v_mfma_f32_16x16x32_bf16 v[20:23], v[170:173], v[194:197], v[20:23]
	v_mfma_f32_16x16x32_bf16 v[20:23], v[174:177], v[198:201], v[20:23]
	v_mfma_f32_16x16x32_bf16 v[16:19], v[218:221], v[194:197], v[16:19]
	v_mfma_f32_16x16x32_bf16 v[16:19], v[222:225], v[198:201], v[16:19]
	v_mfma_f32_16x16x32_bf16 v[24:27], v[210:213], v[194:197], v[24:27]
	v_mfma_f32_16x16x32_bf16 v[24:27], v[214:217], v[198:201], v[24:27]
	v_mfma_f32_16x16x32_bf16 v[8:11], v[210:213], v[202:205], v[8:11]
	v_mfma_f32_16x16x32_bf16 v[8:11], v[214:217], v[206:209], v[8:11]
	v_mfma_f32_16x16x32_bf16 v[0:3], v[218:221], v[202:205], v[0:3]
	v_mfma_f32_16x16x32_bf16 v[0:3], v[222:225], v[206:209], v[0:3]
	v_mfma_f32_16x16x32_bf16 v[4:7], v[170:173], v[202:205], v[4:7]
	v_mfma_f32_16x16x32_bf16 v[4:7], v[174:177], v[206:209], v[4:7]
	v_mfma_f32_16x16x32_bf16 v[12:15], v[142:145], v[202:205], v[12:15]
	v_mfma_f32_16x16x32_bf16 v[12:15], v[166:169], v[206:209], v[12:15]
	s_add_i32 s3, s3, 2
	s_addk_i32 s5, 0x80
	s_add_u32 s14, s14, 0x100
	s_addc_u32 s15, s15, 0
	s_cmp_gt_u32 s3, 13
	s_barrier
	s_cbranch_scc0 .LBB0_236
	v_exp_f32_e64 v144, -v124
	v_exp_f32_e64 v145, -v125
	v_exp_f32_e64 v146, -v126
	v_exp_f32_e64 v147, -v127
	v_pk_mul_f32 v[122:123], v[126:127], v[122:123]
	v_pk_add_f32 v[144:145], v[144:145], 1.0 op_sel_hi:[1,0]
	v_pk_mul_f32 v[120:121], v[124:125], v[120:121]
	v_pk_add_f32 v[146:147], v[146:147], 1.0 op_sel_hi:[1,0]
	v_rcp_f32_e32 v144, v144
	v_rcp_f32_e32 v145, v145
	v_rcp_f32_e32 v146, v146
	v_rcp_f32_e32 v147, v147
	v_exp_f32_e64 v124, -v116
	v_exp_f32_e64 v125, -v117
	v_exp_f32_e64 v126, -v118
	v_exp_f32_e64 v127, -v119
	v_pk_mul_f32 v[120:121], v[144:145], v[120:121]
	v_pk_mul_f32 v[122:123], v[146:147], v[122:123]
	v_cvt_pk_bf16_f32 v120, v120, v121
	v_pk_mul_f32 v[114:115], v[118:119], v[114:115]
	v_cvt_pk_bf16_f32 v121, v122, v123
	v_pk_add_f32 v[122:123], v[124:125], 1.0 op_sel_hi:[1,0]
	v_pk_add_f32 v[124:125], v[126:127], 1.0 op_sel_hi:[1,0]
	v_rcp_f32_e32 v122, v122
	v_rcp_f32_e32 v123, v123
	v_rcp_f32_e32 v124, v124
	v_rcp_f32_e32 v125, v125
	v_pk_mul_f32 v[112:113], v[116:117], v[112:113]
	v_pk_mul_f32 v[106:107], v[110:111], v[106:107]
	v_pk_mul_f32 v[112:113], v[122:123], v[112:113]
	v_pk_mul_f32 v[114:115], v[124:125], v[114:115]
	v_cvt_pk_bf16_f32 v122, v112, v113
	v_exp_f32_e64 v112, -v108
	v_cvt_pk_bf16_f32 v123, v114, v115
	v_exp_f32_e64 v113, -v109
	v_exp_f32_e64 v114, -v110
	v_exp_f32_e64 v115, -v111
	v_pk_mul_f32 v[104:105], v[108:109], v[104:105]
	v_pk_add_f32 v[112:113], v[112:113], 1.0 op_sel_hi:[1,0]
	v_exp_f32_e64 v108, -v100
	v_pk_add_f32 v[114:115], v[114:115], 1.0 op_sel_hi:[1,0]
	v_rcp_f32_e32 v112, v112
	v_rcp_f32_e32 v113, v113
	v_rcp_f32_e32 v114, v114
	v_rcp_f32_e32 v115, v115
	v_exp_f32_e64 v109, -v101
	v_exp_f32_e64 v110, -v102
	v_exp_f32_e64 v111, -v103
	v_pk_mul_f32 v[104:105], v[112:113], v[104:105]
	v_pk_mul_f32 v[106:107], v[114:115], v[106:107]
	v_cvt_pk_bf16_f32 v104, v104, v105
	v_pk_mul_f32 v[98:99], v[102:103], v[98:99]
	v_cvt_pk_bf16_f32 v105, v106, v107
	v_pk_add_f32 v[106:107], v[108:109], 1.0 op_sel_hi:[1,0]
; template <int N, int K, int EPI>
; __device__ void gemm_phase(const u16* __restrict__ A, const u16* __restrict__ Bt, const EpiArgs ea, char* smem, int tid) {
;     ...
;         for (int ai = 0; ai < 2; ++ai)
; #pragma unroll
;           for (int m = 0; m < 4; ++m) {
;             const int row = brow + ai * HALF + wr * 64 + m * 16 + fr_e;
;             const int col = pn * 128 + wc * 32 + fq_e * 8;
;             u32x4 o;
; #pragma unroll
;             for (int n = 0; n < 2; ++n) {
;               const f32x4 t4 = acc[ai][0][m][n], u4 = acc[ai][1][m][n];
;               f32x2 tl = {t4[0], t4[1]}, th = {t4[2], t4[3]}, ul = {u4[0], u4[1]}, uh = {u4[2], u4[3]};
;               f32x2 el = {__builtin_amdgcn_exp2f(-t4[0]), __builtin_amdgcn_exp2f(-t4[1])};
;               f32x2 eh = {__builtin_amdgcn_exp2f(-t4[2]), __builtin_amdgcn_exp2f(-t4[3])};
;               el = el + 1.f; eh = eh + 1.f;
;               f32x2 rl = {__builtin_amdgcn_rcpf(el[0]), __builtin_amdgcn_rcpf(el[1])};
;               f32x2 rh = {__builtin_amdgcn_rcpf(eh[0]), __builtin_amdgcn_rcpf(eh[1])};
;               const f32x2 hl = tl * ul * rl, hh2 = th * uh * rh;
;               o[2 * n] = pk_bf16(hl[0], hl[1]); o[2 * n + 1] = pk_bf16(hh2[0], hh2[1]);
;             }
;             *(u32x4*)(h + (size_t)row * FF + col) = o;
	v_pk_add_f32 v[108:109], v[110:111], 1.0 op_sel_hi:[1,0]
	v_rcp_f32_e32 v106, v106
	v_rcp_f32_e32 v107, v107
	v_rcp_f32_e32 v108, v108
	v_rcp_f32_e32 v109, v109
	v_pk_mul_f32 v[96:97], v[100:101], v[96:97]
	v_pk_mul_f32 v[90:91], v[94:95], v[90:91]
	v_pk_mul_f32 v[96:97], v[106:107], v[96:97]
	v_pk_mul_f32 v[98:99], v[108:109], v[98:99]
	v_cvt_pk_bf16_f32 v106, v96, v97
	v_exp_f32_e64 v96, -v92
	v_cvt_pk_bf16_f32 v107, v98, v99
	v_exp_f32_e64 v97, -v93
	v_exp_f32_e64 v98, -v94
	v_exp_f32_e64 v99, -v95
	v_pk_mul_f32 v[88:89], v[92:93], v[88:89]
	v_pk_add_f32 v[96:97], v[96:97], 1.0 op_sel_hi:[1,0]
	v_exp_f32_e64 v92, -v84
	v_pk_add_f32 v[98:99], v[98:99], 1.0 op_sel_hi:[1,0]
	v_rcp_f32_e32 v96, v96
	v_rcp_f32_e32 v97, v97
	v_rcp_f32_e32 v98, v98
	v_rcp_f32_e32 v99, v99
	v_exp_f32_e64 v93, -v85
	v_exp_f32_e64 v94, -v86
	v_exp_f32_e64 v95, -v87
	v_pk_mul_f32 v[88:89], v[96:97], v[88:89]
	v_pk_mul_f32 v[90:91], v[98:99], v[90:91]
	v_cvt_pk_bf16_f32 v88, v88, v89
	v_pk_mul_f32 v[82:83], v[86:87], v[82:83]
	v_cvt_pk_bf16_f32 v89, v90, v91
	v_pk_add_f32 v[90:91], v[92:93], 1.0 op_sel_hi:[1,0]
	v_pk_add_f32 v[92:93], v[94:95], 1.0 op_sel_hi:[1,0]
	v_rcp_f32_e32 v90, v90
	v_rcp_f32_e32 v91, v91
	v_rcp_f32_e32 v92, v92
	v_rcp_f32_e32 v93, v93
	v_pk_mul_f32 v[80:81], v[84:85], v[80:81]
	v_pk_mul_f32 v[74:75], v[78:79], v[74:75]
	v_pk_mul_f32 v[80:81], v[90:91], v[80:81]
	v_pk_mul_f32 v[82:83], v[92:93], v[82:83]
	v_cvt_pk_bf16_f32 v90, v80, v81
	v_exp_f32_e64 v80, -v76
	v_cvt_pk_bf16_f32 v91, v82, v83
	v_exp_f32_e64 v81, -v77
	v_exp_f32_e64 v82, -v78
	v_exp_f32_e64 v83, -v79
	v_pk_mul_f32 v[72:73], v[76:77], v[72:73]
	v_pk_add_f32 v[80:81], v[80:81], 1.0 op_sel_hi:[1,0]
	v_exp_f32_e64 v76, -v68
	v_pk_add_f32 v[82:83], v[82:83], 1.0 op_sel_hi:[1,0]
	v_rcp_f32_e32 v80, v80
	v_rcp_f32_e32 v81, v81
	v_rcp_f32_e32 v82, v82
	v_rcp_f32_e32 v83, v83
	v_exp_f32_e64 v77, -v69
	v_exp_f32_e64 v78, -v70
	v_exp_f32_e64 v79, -v71
	v_pk_mul_f32 v[72:73], v[80:81], v[72:73]
	v_pk_mul_f32 v[74:75], v[82:83], v[74:75]
	v_cvt_pk_bf16_f32 v72, v72, v73
	s_lshl_b32 s3, s77, 8
	v_cvt_pk_bf16_f32 v73, v74, v75
	v_pk_add_f32 v[74:75], v[76:77], 1.0 op_sel_hi:[1,0]
	v_pk_add_f32 v[76:77], v[78:79], 1.0 op_sel_hi:[1,0]
	v_rcp_f32_e32 v74, v74
	v_rcp_f32_e32 v76, v76
	v_rcp_f32_e32 v77, v77
	v_rcp_f32_e32 v75, v75
	v_mov_b32_e32 v128, v132
	v_mov_b32_e32 v129, v131
	s_add_i32 s3, s3, s43
	v_pk_mul_f32 v[66:67], v[70:71], v[66:67]
	v_add_u32_e32 v142, s3, v129
	s_lshl_b32 s3, s73, 7
	s_or_b32 s3, s3, s66
	v_pk_mul_f32 v[64:65], v[68:69], v[64:65]
	v_pk_mul_f32 v[66:67], v[76:77], v[66:67]
	v_lshl_add_u32 v128, v128, 3, s3
	v_pk_mul_f32 v[64:65], v[74:75], v[64:65]
	v_cvt_pk_bf16_f32 v75, v66, v67
	v_exp_f32_e64 v66, -v60
	v_exp_f32_e64 v67, -v61
	v_exp_f32_e64 v68, -v62
	v_exp_f32_e64 v69, -v63
	v_ashrrev_i32_e32 v129, 31, v128
	v_lshl_add_u64 v[128:129], v[128:129], 1, s[80:81]
	v_cvt_pk_bf16_f32 v74, v64, v65
	v_add_u32_e32 v64, 48, v142
	v_mad_i64_i32 v[64:65], s[10:11], v64, s68, v[128:129]
	global_store_dwordx4 v[64:65], v[72:75], off
	v_pk_add_f32 v[64:65], v[66:67], 1.0 op_sel_hi:[1,0]
	v_pk_add_f32 v[66:67], v[68:69], 1.0 op_sel_hi:[1,0]
	v_rcp_f32_e32 v64, v64
	v_rcp_f32_e32 v65, v65
	v_rcp_f32_e32 v66, v66
	v_rcp_f32_e32 v67, v67
	v_pk_mul_f32 v[58:59], v[62:63], v[58:59]
	v_pk_mul_f32 v[56:57], v[60:61], v[56:57]
	v_exp_f32_e64 v60, -v52
	v_exp_f32_e64 v61, -v53
	v_exp_f32_e64 v62, -v54
	v_exp_f32_e64 v63, -v55
	v_pk_mul_f32 v[56:57], v[64:65], v[56:57]
	v_pk_mul_f32 v[58:59], v[66:67], v[58:59]
	v_cvt_pk_bf16_f32 v56, v56, v57
	v_pk_mul_f32 v[50:51], v[54:55], v[50:51]
	v_cvt_pk_bf16_f32 v57, v58, v59
	v_pk_add_f32 v[58:59], v[60:61], 1.0 op_sel_hi:[1,0]
	v_pk_add_f32 v[60:61], v[62:63], 1.0 op_sel_hi:[1,0]
	v_rcp_f32_e32 v58, v58
	v_rcp_f32_e32 v59, v59
	v_rcp_f32_e32 v60, v60
	v_rcp_f32_e32 v61, v61
	v_pk_mul_f32 v[48:49], v[52:53], v[48:49]
	v_pk_mul_f32 v[42:43], v[46:47], v[42:43]
	v_pk_mul_f32 v[48:49], v[58:59], v[48:49]
	v_pk_mul_f32 v[50:51], v[60:61], v[50:51]
	v_cvt_pk_bf16_f32 v58, v48, v49
	v_exp_f32_e64 v48, -v44
	v_cvt_pk_bf16_f32 v59, v50, v51
	v_exp_f32_e64 v49, -v45
	v_exp_f32_e64 v50, -v46
	v_exp_f32_e64 v51, -v47
	v_pk_mul_f32 v[40:41], v[44:45], v[40:41]
; #define WAIT_V(n) asm volatile("s_waitcnt vmcnt(" #n ")" ::: "memory")
; #define BAR __builtin_amdgcn_s_barrier()
; template <int N, int K, int EPI>
; __device__ void gemm_phase(const u16* __restrict__ A, const u16* __restrict__ Bt, const EpiArgs ea, char* smem, int tid) {
;     ...
;         for (int ai = 0; ai < 2; ++ai)
; #pragma unroll
;           for (int m = 0; m < 4; ++m) {
;             const int row = brow + ai * HALF + wr * 64 + m * 16 + fr_e;
;             const int col = pn * 128 + wc * 32 + fq_e * 8;
;             u32x4 o;
; #pragma unroll
;             for (int n = 0; n < 2; ++n) {
;               const f32x4 t4 = acc[ai][0][m][n], u4 = acc[ai][1][m][n];
;               f32x2 tl = {t4[0], t4[1]}, th = {t4[2], t4[3]}, ul = {u4[0], u4[1]}, uh = {u4[2], u4[3]};
;               f32x2 el = {__builtin_amdgcn_exp2f(-t4[0]), __builtin_amdgcn_exp2f(-t4[1])};
;               f32x2 eh = {__builtin_amdgcn_exp2f(-t4[2]), __builtin_amdgcn_exp2f(-t4[3])};
;               el = el + 1.f; eh = eh + 1.f;
;               f32x2 rl = {__builtin_amdgcn_rcpf(el[0]), __builtin_amdgcn_rcpf(el[1])};
;               f32x2 rh = {__builtin_amdgcn_rcpf(eh[0]), __builtin_amdgcn_rcpf(eh[1])};
;               const f32x2 hl = tl * ul * rl, hh2 = th * uh * rh;
;               o[2 * n] = pk_bf16(hl[0], hl[1]); o[2 * n + 1] = pk_bf16(hh2[0], hh2[1]);
;             }
;             *(u32x4*)(h + (size_t)row * FF + col) = o;
;     ...
;     if (!has_next) break;
; #pragma unroll
;     for (int ai = 0; ai < 2; ++ai)
; #pragma unroll
;       for (int bj = 0; bj < 2; ++bj)
; #pragma unroll
;         for (int m = 0; m < 4; ++m)
; #pragma unroll
;           for (int n = 0; n < 2; ++n) acc[ai][bj][m][n] = f32x4{0.f, 0.f, 0.f, 0.f};
;     v = vn; pm = pmn; pn = pnn; Ab = Abn; Bb = Bbn;
;   }
;   WAIT_V(0);
;   if (wr == 0) BAR;
;   __syncthreads();
	v_pk_add_f32 v[48:49], v[48:49], 1.0 op_sel_hi:[1,0]
	v_exp_f32_e64 v44, -v36
	v_pk_add_f32 v[50:51], v[50:51], 1.0 op_sel_hi:[1,0]
	v_rcp_f32_e32 v48, v48
	v_rcp_f32_e32 v49, v49
	v_rcp_f32_e32 v50, v50
	v_rcp_f32_e32 v51, v51
	v_exp_f32_e64 v45, -v37
	v_exp_f32_e64 v46, -v38
	v_exp_f32_e64 v47, -v39
	v_pk_mul_f32 v[40:41], v[48:49], v[40:41]
	v_pk_mul_f32 v[42:43], v[50:51], v[42:43]
	v_cvt_pk_bf16_f32 v40, v40, v41
	v_pk_mul_f32 v[34:35], v[38:39], v[34:35]
	v_cvt_pk_bf16_f32 v41, v42, v43
	v_pk_add_f32 v[42:43], v[44:45], 1.0 op_sel_hi:[1,0]
	v_pk_add_f32 v[44:45], v[46:47], 1.0 op_sel_hi:[1,0]
	v_rcp_f32_e32 v42, v42
	v_rcp_f32_e32 v43, v43
	v_rcp_f32_e32 v44, v44
	v_rcp_f32_e32 v45, v45
	v_pk_mul_f32 v[32:33], v[36:37], v[32:33]
	v_pk_mul_f32 v[26:27], v[30:31], v[26:27]
	v_pk_mul_f32 v[32:33], v[42:43], v[32:33]
	v_pk_mul_f32 v[34:35], v[44:45], v[34:35]
	v_cvt_pk_bf16_f32 v42, v32, v33
	v_exp_f32_e64 v32, -v28
	v_cvt_pk_bf16_f32 v43, v34, v35
	v_exp_f32_e64 v33, -v29
	v_exp_f32_e64 v34, -v30
	v_exp_f32_e64 v35, -v31
	v_pk_mul_f32 v[24:25], v[28:29], v[24:25]
	v_pk_add_f32 v[32:33], v[32:33], 1.0 op_sel_hi:[1,0]
	v_exp_f32_e64 v28, -v20
	v_pk_add_f32 v[34:35], v[34:35], 1.0 op_sel_hi:[1,0]
	v_rcp_f32_e32 v32, v32
	v_rcp_f32_e32 v33, v33
	v_rcp_f32_e32 v34, v34
	v_rcp_f32_e32 v35, v35
	v_exp_f32_e64 v29, -v21
	v_exp_f32_e64 v30, -v22
	v_exp_f32_e64 v31, -v23
	v_pk_mul_f32 v[24:25], v[32:33], v[24:25]
	v_pk_mul_f32 v[26:27], v[34:35], v[26:27]
	v_cvt_pk_bf16_f32 v24, v24, v25
	v_pk_mul_f32 v[18:19], v[22:23], v[18:19]
	v_cvt_pk_bf16_f32 v25, v26, v27
	v_pk_add_f32 v[26:27], v[28:29], 1.0 op_sel_hi:[1,0]
	v_pk_add_f32 v[28:29], v[30:31], 1.0 op_sel_hi:[1,0]
	v_rcp_f32_e32 v26, v26
	v_rcp_f32_e32 v27, v27
	v_rcp_f32_e32 v28, v28
	v_rcp_f32_e32 v29, v29
	v_pk_mul_f32 v[16:17], v[20:21], v[16:17]
	v_pk_mul_f32 v[8:9], v[12:13], v[8:9]
	v_pk_mul_f32 v[16:17], v[26:27], v[16:17]
	v_pk_mul_f32 v[18:19], v[28:29], v[18:19]
	v_cvt_pk_bf16_f32 v26, v16, v17
	v_exp_f32_e64 v16, -v12
	v_cvt_pk_bf16_f32 v27, v18, v19
	v_exp_f32_e64 v17, -v13
	v_exp_f32_e64 v18, -v14
	v_exp_f32_e64 v19, -v15
	v_exp_f32_e64 v12, -v4
	v_pk_add_f32 v[16:17], v[16:17], 1.0 op_sel_hi:[1,0]
	v_exp_f32_e64 v13, -v5
	v_pk_add_f32 v[18:19], v[18:19], 1.0 op_sel_hi:[1,0]
	v_rcp_f32_e32 v16, v16
	v_rcp_f32_e32 v17, v17
	v_rcp_f32_e32 v18, v18
	v_rcp_f32_e32 v19, v19
	v_pk_mul_f32 v[10:11], v[14:15], v[10:11]
	v_pk_mul_f32 v[8:9], v[16:17], v[8:9]
	v_exp_f32_e64 v14, -v6
	v_pk_mul_f32 v[10:11], v[18:19], v[10:11]
	v_exp_f32_e64 v15, -v7
	v_cvt_pk_bf16_f32 v8, v8, v9
	v_cvt_pk_bf16_f32 v9, v10, v11
	v_pk_add_f32 v[10:11], v[12:13], 1.0 op_sel_hi:[1,0]
	v_pk_add_f32 v[12:13], v[14:15], 1.0 op_sel_hi:[1,0]
	v_rcp_f32_e32 v10, v10
	v_rcp_f32_e32 v11, v11
	v_pk_mul_f32 v[0:1], v[4:5], v[0:1]
	v_rcp_f32_e32 v12, v12
	v_rcp_f32_e32 v13, v13
	v_pk_mul_f32 v[0:1], v[10:11], v[0:1]
	v_add_u32_e32 v100, 16, v142
	v_add_u32_e32 v84, 32, v142
	v_add_u32_e32 v70, 0x80, v142
	v_add_u32_e32 v36, 0x90, v142
	v_add_u32_e32 v20, 0xa0, v142
	v_cvt_pk_bf16_f32 v10, v0, v1
	v_add_u32_e32 v0, 0xb0, v142
	v_mad_i64_i32 v[116:117], s[10:11], v142, s68, v[128:129]
	v_mad_i64_i32 v[100:101], s[10:11], v100, s68, v[128:129]
	v_mad_i64_i32 v[84:85], s[10:11], v84, s68, v[128:129]
	v_mad_i64_i32 v[52:53], s[10:11], v70, s68, v[128:129]
	v_mad_i64_i32 v[36:37], s[10:11], v36, s68, v[128:129]
	v_mad_i64_i32 v[20:21], s[10:11], v20, s68, v[128:129]
	v_mad_i64_i32 v[0:1], s[10:11], v0, s68, v[128:129]
	v_pk_mul_f32 v[2:3], v[6:7], v[2:3]
	s_and_b64 vcc, exec, s[0:1]
	s_mov_b32 s77, s2
	s_mov_b32 s73, s4
	s_mov_b64 s[12:13], s[8:9]
	s_mov_b64 s[10:11], s[6:7]
	global_store_dwordx4 v[116:117], v[120:123], off
	global_store_dwordx4 v[100:101], v[104:107], off
	global_store_dwordx4 v[84:85], v[88:91], off
	global_store_dwordx4 v[52:53], v[56:59], off
	global_store_dwordx4 v[36:37], v[40:43], off
	global_store_dwordx4 v[20:21], v[24:27], off
	v_pk_mul_f32 v[2:3], v[12:13], v[2:3]
	s_nop 0
	v_cvt_pk_bf16_f32 v11, v2, v3
	global_store_dwordx4 v[0:1], v[8:11], off
	s_cbranch_vccz .LBB0_233
	s_setprio 0
	s_waitcnt vmcnt(0)
	v_readlane_b32 s36, v226, 30
	s_cmpk_gt_u32 s22, 0xff
	s_mov_b64 s[34:35], s[96:97]
	v_readlane_b32 s37, v226, 31
	s_cbranch_scc1 .LBB0_240
	s_barrier
